# baseline (speedup 1.0000x reference)
; #define LAS __attribute__((address_space(3)))
; __device__ __forceinline__ unsigned pk2(float lo, float hi) { unsigned r; asm volatile("v_cvt_pk_bf16_f32 %0, %1, %2" : "=v"(r) : "v"(lo), "v"(hi)); return r; }
; __device__ __forceinline__ void p0_transpose_item(const float* W, int K, int N, const float* gain, const float* gain2  , bf16_t* WT, LAS unsigned* scr, int item, int lane) {
;     ...
;     for (int j = 0; j < 8; ++j) {
;         float g0 = 1.f, g1 = 1.f; if (gain) { g0 = gain[k0 + 8 * j + 2 * kq]; g1 = gain[k0 + 8 * j + 2 * kq + 1]; }
; #pragma unroll
;         for (int i = 0; i < 4; ++i) scr[(4 * n4 + i) * 32 + (((j ^ (n4 & 7)) << 2) | kq)] = pk2(r0[j][i] * g0, r1[j][i] * g1);
;     }
;     asm volatile("s_waitcnt lgkmcnt(0)" ::: "memory");
; #pragma unroll
;     for (int it = 0; it < 8; ++it) {
;         const int n = (lane >> 3) + 8 * it, c = lane & 7;
;         const u32x4 v = *(const LAS u32x4*)(scr + n * 32 + ((c ^ ((n >> 2) & 7)) << 2));
;         *(u32x4*)(WT + (size_t)(n0 + n) * K + k0 + 8 * c) = v;
;     }
.LBB0_116:
	s_waitcnt vmcnt(0)
	v_mul_f32_e32 v2, v2, v18
	v_mul_f32_e32 v6, v6, v19
	v_cvt_pk_bf16_f32 v2, v2, v6
	v_add_u32_e32 v6, v93, v86
	ds_write_b32 v6, v2
	v_mul_f32_e32 v2, v3, v18
	v_mul_f32_e32 v3, v7, v19
	v_cvt_pk_bf16_f32 v2, v2, v3
	ds_write_b32 v6, v2 offset:128
	v_mul_f32_e32 v2, v4, v18
	v_mul_f32_e32 v3, v8, v19
	v_cvt_pk_bf16_f32 v2, v2, v3
	ds_write_b32 v6, v2 offset:256
	v_mul_f32_e32 v2, v5, v18
	v_mul_f32_e32 v3, v9, v19
	v_cvt_pk_bf16_f32 v2, v2, v3
	ds_write_b32 v6, v2 offset:384
	v_ashrrev_i32_e32 v81, 31, v80
	s_waitcnt lgkmcnt(0)
	v_lshl_add_u64 v[2:3], v[80:81], 1, v[74:75]
	v_lshlrev_b32_e32 v4, 1, v70
	v_mov_b32_e32 v5, v69
	v_lshl_add_u64 v[10:11], v[2:3], 0, v[4:5]
	ds_read_b128 v[2:5], v95
	v_or_b32_e32 v6, v78, v94
	v_ashrrev_i32_e32 v7, 31, v6
	v_lshlrev_b64 v[6:7], 12, v[6:7]
	v_lshl_add_u64 v[12:13], v[10:11], 0, v[6:7]
	ds_read_b128 v[6:9], v97
	s_waitcnt lgkmcnt(1)
	global_store_dwordx4 v[12:13], v[2:5], off sc0 sc1
	s_nop 1
	v_or_b32_e32 v2, v78, v96
	v_ashrrev_i32_e32 v3, 31, v2
	v_lshlrev_b64 v[2:3], 12, v[2:3]
	v_lshl_add_u64 v[2:3], v[10:11], 0, v[2:3]
	s_waitcnt lgkmcnt(0)
	global_store_dwordx4 v[2:3], v[6:9], off sc0 sc1
	ds_read_b128 v[2:5], v99
	s_nop 0
	v_or_b32_e32 v6, v78, v98
	v_ashrrev_i32_e32 v7, 31, v6
	v_lshlrev_b64 v[6:7], 12, v[6:7]
	v_lshl_add_u64 v[12:13], v[10:11], 0, v[6:7]
	ds_read_b128 v[6:9], v101
	s_waitcnt lgkmcnt(1)
	global_store_dwordx4 v[12:13], v[2:5], off sc0 sc1
	s_nop 1
	v_or_b32_e32 v2, v78, v100
	v_ashrrev_i32_e32 v3, 31, v2
	v_lshlrev_b64 v[2:3], 12, v[2:3]
	v_lshl_add_u64 v[2:3], v[10:11], 0, v[2:3]
	s_waitcnt lgkmcnt(0)
	global_store_dwordx4 v[2:3], v[6:9], off sc0 sc1
	ds_read_b128 v[2:5], v103
	s_nop 0
	v_or_b32_e32 v6, v78, v102
	v_ashrrev_i32_e32 v7, 31, v6
	v_lshlrev_b64 v[6:7], 12, v[6:7]
	v_lshl_add_u64 v[12:13], v[10:11], 0, v[6:7]
	ds_read_b128 v[6:9], v105
	s_waitcnt lgkmcnt(1)
	global_store_dwordx4 v[12:13], v[2:5], off sc0 sc1
	s_nop 1
	v_or_b32_e32 v2, v78, v104
	v_ashrrev_i32_e32 v3, 31, v2
	v_lshlrev_b64 v[2:3], 12, v[2:3]
	v_lshl_add_u64 v[2:3], v[10:11], 0, v[2:3]
	s_waitcnt lgkmcnt(0)
	global_store_dwordx4 v[2:3], v[6:9], off sc0 sc1
	ds_read_b128 v[2:5], v107
	s_nop 0
	v_or_b32_e32 v6, v78, v106
	v_ashrrev_i32_e32 v7, 31, v6
	v_lshlrev_b64 v[6:7], 12, v[6:7]
	v_lshl_add_u64 v[12:13], v[10:11], 0, v[6:7]
	ds_read_b128 v[6:9], v109
	s_waitcnt lgkmcnt(1)
	global_store_dwordx4 v[12:13], v[2:5], off sc0 sc1
	s_nop 1
	v_or_b32_e32 v2, v78, v108
	v_ashrrev_i32_e32 v3, 31, v2
	v_lshlrev_b64 v[2:3], 12, v[2:3]
	v_lshl_add_u64 v[2:3], v[10:11], 0, v[2:3]
	s_waitcnt lgkmcnt(0)
	global_store_dwordx4 v[2:3], v[6:9], off sc0 sc1
	s_waitcnt lgkmcnt(0)

; #define LAS __attribute__((address_space(3)))
; __device__ __forceinline__ unsigned pk2(float lo, float hi) { unsigned r; asm volatile("v_cvt_pk_bf16_f32 %0, %1, %2" : "=v"(r) : "v"(lo), "v"(hi)); return r; }
; __device__ __forceinline__ void p0_transpose_item(const float* W, int K, int N, const float* gain, const float* gain2  , bf16_t* WT, LAS unsigned* scr, int item, int lane) {
;     ...
;     for (int j = 0; j < 8; ++j) {
;         float g0 = 1.f, g1 = 1.f; if (gain) { g0 = gain[k0 + 8 * j + 2 * kq]; g1 = gain[k0 + 8 * j + 2 * kq + 1]; }
; #pragma unroll
;         for (int i = 0; i < 4; ++i) scr[(4 * n4 + i) * 32 + (((j ^ (n4 & 7)) << 2) | kq)] = pk2(r0[j][i] * g0, r1[j][i] * g1);
;     }
;     asm volatile("s_waitcnt lgkmcnt(0)" ::: "memory");
; #pragma unroll
;     for (int it = 0; it < 8; ++it) {
;         const int n = (lane >> 3) + 8 * it, c = lane & 7;
;         const u32x4 v = *(const LAS u32x4*)(scr + n * 32 + ((c ^ ((n >> 2) & 7)) << 2));
;         *(u32x4*)(WT + (size_t)(n0 + n) * K + k0 + 8 * c) = v;
;     }
.LBB0_138:
	s_or_b64 exec, exec, s[34:35]
	s_waitcnt vmcnt(0)
	v_mul_f32_e32 v2, v2, v18
	v_mul_f32_e32 v6, v6, v19
	v_cvt_pk_bf16_f32 v2, v2, v6
	v_add_u32_e32 v6, v93, v86
	ds_write_b32 v6, v2
	v_mul_f32_e32 v2, v3, v18
	v_mul_f32_e32 v3, v7, v19
	v_cvt_pk_bf16_f32 v2, v2, v3
	ds_write_b32 v6, v2 offset:128
	v_mul_f32_e32 v2, v4, v18
	v_mul_f32_e32 v3, v8, v19
	v_cvt_pk_bf16_f32 v2, v2, v3
	ds_write_b32 v6, v2 offset:256
	v_mul_f32_e32 v2, v5, v18
	v_mul_f32_e32 v3, v9, v19
	v_cvt_pk_bf16_f32 v2, v2, v3
	ds_write_b32 v6, v2 offset:384
	v_lshlrev_b32_e32 v2, 1, v85
	v_mov_b32_e32 v3, v69
	v_lshl_add_u64 v[2:3], v[74:75], 0, v[2:3]
	v_lshlrev_b32_e32 v4, 1, v70
	v_mov_b32_e32 v5, v69
	s_waitcnt lgkmcnt(0)
	v_lshl_add_u64 v[2:3], v[2:3], 0, v[4:5]
	v_lshl_add_u64 v[10:11], v[2:3], 0, s[18:19]
	ds_read_b128 v[2:5], v95
	v_or_b32_e32 v6, v84, v94
	v_lshlrev_b32_e32 v6, 12, v6
	v_mov_b32_e32 v7, v69
	v_lshl_add_u64 v[12:13], v[10:11], 0, v[6:7]
	ds_read_b128 v[6:9], v97
	s_waitcnt lgkmcnt(1)
	global_store_dwordx4 v[12:13], v[2:5], off sc0 sc1
	s_nop 1
	v_or_b32_e32 v2, v84, v96
	v_lshlrev_b32_e32 v2, 12, v2
	v_mov_b32_e32 v3, v69
	v_lshl_add_u64 v[2:3], v[10:11], 0, v[2:3]
	s_waitcnt lgkmcnt(0)
	global_store_dwordx4 v[2:3], v[6:9], off sc0 sc1
	ds_read_b128 v[2:5], v99
	s_nop 0
	v_or_b32_e32 v6, v84, v98
	v_lshlrev_b32_e32 v6, 12, v6
	v_mov_b32_e32 v7, v69
	v_lshl_add_u64 v[12:13], v[10:11], 0, v[6:7]
	ds_read_b128 v[6:9], v101
	s_waitcnt lgkmcnt(1)
	global_store_dwordx4 v[12:13], v[2:5], off sc0 sc1
	s_nop 1
	v_or_b32_e32 v2, v84, v100
	v_lshlrev_b32_e32 v2, 12, v2
	v_mov_b32_e32 v3, v69
	v_lshl_add_u64 v[2:3], v[10:11], 0, v[2:3]
	s_waitcnt lgkmcnt(0)
	global_store_dwordx4 v[2:3], v[6:9], off sc0 sc1
	ds_read_b128 v[2:5], v103
	s_nop 0
	v_or_b32_e32 v6, v84, v102
	v_lshlrev_b32_e32 v6, 12, v6
	v_mov_b32_e32 v7, v69
	v_lshl_add_u64 v[12:13], v[10:11], 0, v[6:7]
	ds_read_b128 v[6:9], v105
	s_waitcnt lgkmcnt(1)
	global_store_dwordx4 v[12:13], v[2:5], off sc0 sc1
	s_nop 1
	v_or_b32_e32 v2, v84, v104
	v_lshlrev_b32_e32 v2, 12, v2
	v_mov_b32_e32 v3, v69
	v_lshl_add_u64 v[2:3], v[10:11], 0, v[2:3]
	s_waitcnt lgkmcnt(0)
	global_store_dwordx4 v[2:3], v[6:9], off sc0 sc1
	ds_read_b128 v[2:5], v107
	s_nop 0
	v_or_b32_e32 v6, v84, v106
	v_lshlrev_b32_e32 v6, 12, v6
	v_mov_b32_e32 v7, v69
	v_lshl_add_u64 v[12:13], v[10:11], 0, v[6:7]
	ds_read_b128 v[6:9], v109
	s_waitcnt lgkmcnt(1)
	global_store_dwordx4 v[12:13], v[2:5], off sc0 sc1
	s_nop 1
	v_or_b32_e32 v2, v84, v108
	v_lshlrev_b32_e32 v2, 12, v2
	v_mov_b32_e32 v3, v69
	v_lshl_add_u64 v[2:3], v[10:11], 0, v[2:3]
	s_waitcnt lgkmcnt(0)
	global_store_dwordx4 v[2:3], v[6:9], off sc0 sc1
	s_waitcnt lgkmcnt(0)
; #define LAS __attribute__((address_space(3)))
; __device__ __forceinline__ unsigned pk2(float lo, float hi) { unsigned r; asm volatile("v_cvt_pk_bf16_f32 %0, %1, %2" : "=v"(r) : "v"(lo), "v"(hi)); return r; }
; __device__ __forceinline__ void p0_transpose_item(const float* W, int K, int N, const float* gain, const float* gain2  , bf16_t* WT, LAS unsigned* scr, int item, int lane) {
;     const int nblk = N / 64, kb = item / nblk, nb = item % nblk, k0 = 64 * kb, n0 = 64 * nb;
;     if (gain2 && k0 >= 1024) gain = gain2 - 1024;
;     const int n4 = lane & 15, kq = lane >> 4;
;     f32x4 r0[8], r1[8];
;     const float* src = W + (size_t)(k0 + 2 * kq) * N + n0 + 4 * n4;
; #pragma unroll
;     for (int j = 0; j < 8; ++j) { r0[j] = __builtin_nontemporal_load((const f32x4*)(src + (size_t)(8 * j) * N)); r1[j] = __builtin_nontemporal_load((const f32x4*)(src + (size_t)(8 * j + 1) * N)); }
; #pragma unroll
;     for (int j = 0; j < 8; ++j) {
;         float g0 = 1.f, g1 = 1.f; if (gain) { g0 = gain[k0 + 8 * j + 2 * kq]; g1 = gain[k0 + 8 * j + 2 * kq + 1]; }
; #pragma unroll
;         for (int i = 0; i < 4; ++i) scr[(4 * n4 + i) * 32 + (((j ^ (n4 & 7)) << 2) | kq)] = pk2(r0[j][i] * g0, r1[j][i] * g1);
;     }
;     asm volatile("s_waitcnt lgkmcnt(0)" ::: "memory");
; #pragma unroll
;     for (int it = 0; it < 8; ++it) {
;         const int n = (lane >> 3) + 8 * it, c = lane & 7;
;         const u32x4 v = *(const LAS u32x4*)(scr + n * 32 + ((c ^ ((n >> 2) & 7)) << 2));
;         *(u32x4*)(WT + (size_t)(n0 + n) * K + k0 + 8 * c) = v;
;     }
.LBB0_139:
	s_andn2_saveexec_b64 s[30:31], s[30:31]
	s_cbranch_execz .LBB0_141
	v_lshlrev_b32_e32 v2, 2, v3
	v_sub_u32_e32 v2, v111, v2
	v_lshlrev_b64 v[4:5], 22, v[76:77]
	v_and_b32_e32 v76, 0x3c0, v2
	v_lshlrev_b32_e32 v2, 6, v3
	v_sub_u32_e32 v2, v110, v2
	v_lshl_add_u64 v[4:5], s[62:63], 0, v[4:5]
	v_and_b32_e32 v77, 0x3c0, v2
	v_lshl_or_b32 v2, v76, 12, v112
	v_mov_b32_e32 v3, v69
	v_lshl_add_u64 v[2:3], v[4:5], 0, v[2:3]
	v_lshlrev_b32_e32 v4, 2, v77
	v_mov_b32_e32 v5, v69
	v_lshl_add_u64 v[2:3], v[2:3], 0, v[4:5]
	v_lshl_add_u64 v[58:59], v[2:3], 0, v[68:69]
	s_movk_i32 s34, 0x1000
	v_add_co_u32_e32 v6, vcc, s34, v58
	s_mov_b32 s34, 0x9000
	s_nop 0
	v_addc_co_u32_e32 v7, vcc, 0, v59, vcc
	global_load_dwordx4 v[2:5], v[58:59], off nt
	s_nop 0
	global_load_dwordx4 v[6:9], v[6:7], off nt
	v_add_co_u32_e32 v14, vcc, s34, v58
	s_mov_b32 s34, 0x11000
	s_nop 0
	v_addc_co_u32_e32 v15, vcc, 0, v59, vcc
	global_load_dwordx4 v[10:13], v[14:15], off offset:-4096 nt
	s_nop 0
	global_load_dwordx4 v[14:17], v[14:15], off nt
	v_add_co_u32_e32 v22, vcc, s34, v58
	s_mov_b32 s34, 0x19000
	s_nop 0
	v_addc_co_u32_e32 v23, vcc, 0, v59, vcc
	global_load_dwordx4 v[18:21], v[22:23], off offset:-4096 nt
	s_nop 0
	global_load_dwordx4 v[22:25], v[22:23], off nt
	v_add_co_u32_e32 v30, vcc, s34, v58
	s_mov_b32 s34, 0x21000
	s_nop 0
	v_addc_co_u32_e32 v31, vcc, 0, v59, vcc
	global_load_dwordx4 v[26:29], v[30:31], off offset:-4096 nt
	s_waitcnt lgkmcnt(0)
	global_load_dwordx4 v[30:33], v[30:31], off nt
	v_add_co_u32_e32 v38, vcc, s34, v58
	s_mov_b32 s34, 0x29000
	s_nop 0
	v_addc_co_u32_e32 v39, vcc, 0, v59, vcc
	global_load_dwordx4 v[34:37], v[38:39], off offset:-4096 nt
	s_nop 0
	global_load_dwordx4 v[38:41], v[38:39], off nt
	v_add_co_u32_e32 v46, vcc, s34, v58
	s_mov_b32 s34, 0x31000
	s_nop 0
	v_addc_co_u32_e32 v47, vcc, 0, v59, vcc
	global_load_dwordx4 v[42:45], v[46:47], off offset:-4096 nt
	s_nop 0
	global_load_dwordx4 v[46:49], v[46:47], off nt
	v_add_co_u32_e32 v54, vcc, s34, v58
	v_add_u32_e32 v78, v71, v86
	s_nop 0
	v_addc_co_u32_e32 v55, vcc, 0, v59, vcc
	global_load_dwordx4 v[50:53], v[54:55], off offset:-4096 nt
	s_nop 0
	global_load_dwordx4 v[54:57], v[54:55], off nt
	v_add_co_u32_e32 v62, vcc, s85, v58
	v_add_u32_e32 v79, v87, v86
	s_nop 0
	v_addc_co_u32_e32 v63, vcc, 0, v59, vcc
	global_load_dwordx4 v[58:61], v[62:63], off offset:-4096 nt
	s_nop 0
	global_load_dwordx4 v[62:65], v[62:63], off nt
	v_add_u32_e32 v80, v88, v86
	v_add_u32_e32 v81, v89, v86
	v_add_u32_e32 v82, v90, v86
	s_waitcnt vmcnt(14)
	v_cvt_pk_bf16_f32 v2, v2, v6
	ds_write_b32 v78, v2
	v_cvt_pk_bf16_f32 v2, v3, v7
	ds_write_b32 v78, v2 offset:128
	v_cvt_pk_bf16_f32 v2, v4, v8
	ds_write_b32 v78, v2 offset:256
	v_cvt_pk_bf16_f32 v2, v5, v9
	ds_write_b32 v78, v2 offset:384
	s_waitcnt vmcnt(12)
	v_cvt_pk_bf16_f32 v2, v10, v14
	ds_write_b32 v79, v2
	v_cvt_pk_bf16_f32 v2, v11, v15
	ds_write_b32 v79, v2 offset:128
	v_cvt_pk_bf16_f32 v2, v12, v16
	ds_write_b32 v79, v2 offset:256
	v_cvt_pk_bf16_f32 v2, v13, v17
	ds_write_b32 v79, v2 offset:384
	s_waitcnt vmcnt(10)
	v_cvt_pk_bf16_f32 v2, v18, v22
	ds_write_b32 v80, v2
	v_cvt_pk_bf16_f32 v2, v19, v23
	ds_write_b32 v80, v2 offset:128
	v_cvt_pk_bf16_f32 v2, v20, v24
	ds_write_b32 v80, v2 offset:256
	v_cvt_pk_bf16_f32 v2, v21, v25
	ds_write_b32 v80, v2 offset:384
	s_waitcnt vmcnt(8)
	v_cvt_pk_bf16_f32 v2, v26, v30
	ds_write_b32 v81, v2
	v_cvt_pk_bf16_f32 v2, v27, v31
	ds_write_b32 v81, v2 offset:128
	v_cvt_pk_bf16_f32 v2, v28, v32
	ds_write_b32 v81, v2 offset:256
	v_cvt_pk_bf16_f32 v2, v29, v33
	ds_write_b32 v81, v2 offset:384
	s_waitcnt vmcnt(6)
	v_cvt_pk_bf16_f32 v2, v34, v38
	ds_write_b32 v82, v2
	v_cvt_pk_bf16_f32 v2, v35, v39
	ds_write_b32 v82, v2 offset:128
	v_cvt_pk_bf16_f32 v2, v36, v40
	ds_write_b32 v82, v2 offset:256
	v_cvt_pk_bf16_f32 v2, v37, v41
	ds_write_b32 v82, v2 offset:384
	s_waitcnt vmcnt(4)
	v_cvt_pk_bf16_f32 v2, v42, v46
	v_add_u32_e32 v3, v91, v86
	ds_write_b32 v3, v2
	v_cvt_pk_bf16_f32 v2, v43, v47
	ds_write_b32 v3, v2 offset:128
	v_cvt_pk_bf16_f32 v2, v44, v48
	ds_write_b32 v3, v2 offset:256
	v_cvt_pk_bf16_f32 v2, v45, v49
	ds_write_b32 v3, v2 offset:384
	s_waitcnt vmcnt(2)
	v_cvt_pk_bf16_f32 v2, v50, v54
	v_add_u32_e32 v3, v92, v86
	ds_write_b32 v3, v2
	v_cvt_pk_bf16_f32 v2, v51, v55
	ds_write_b32 v3, v2 offset:128
	v_cvt_pk_bf16_f32 v2, v52, v56
	ds_write_b32 v3, v2 offset:256
	v_cvt_pk_bf16_f32 v2, v53, v57
	ds_write_b32 v3, v2 offset:384
	s_waitcnt vmcnt(0)
	v_cvt_pk_bf16_f32 v2, v58, v62
	v_add_u32_e32 v3, v93, v86
	ds_write_b32 v3, v2
	v_cvt_pk_bf16_f32 v2, v59, v63
	ds_write_b32 v3, v2 offset:128
	v_cvt_pk_bf16_f32 v2, v60, v64
	ds_write_b32 v3, v2 offset:256
	v_cvt_pk_bf16_f32 v2, v61, v65
	ds_write_b32 v3, v2 offset:384
	v_lshlrev_b32_e32 v2, 1, v76
	v_mov_b32_e32 v3, v69
	v_lshl_add_u64 v[2:3], v[74:75], 0, v[2:3]
	v_lshlrev_b32_e32 v4, 1, v70
	v_mov_b32_e32 v5, v69
	s_waitcnt lgkmcnt(0)
	v_lshl_add_u64 v[2:3], v[2:3], 0, v[4:5]
	v_lshl_add_u64 v[10:11], v[2:3], 0, s[20:21]
	ds_read_b128 v[2:5], v95
	v_or_b32_e32 v6, v77, v94
	v_lshlrev_b32_e32 v6, 11, v6
	v_mov_b32_e32 v7, v69
	v_lshl_add_u64 v[12:13], v[10:11], 0, v[6:7]
	ds_read_b128 v[6:9], v97
	s_waitcnt lgkmcnt(1)
	global_store_dwordx4 v[12:13], v[2:5], off sc0 sc1
	s_nop 1
	v_or_b32_e32 v2, v77, v96
	v_lshlrev_b32_e32 v2, 11, v2
	v_mov_b32_e32 v3, v69
	v_lshl_add_u64 v[2:3], v[10:11], 0, v[2:3]
	s_waitcnt lgkmcnt(0)
	global_store_dwordx4 v[2:3], v[6:9], off sc0 sc1
	ds_read_b128 v[2:5], v99
	s_nop 0
	v_or_b32_e32 v6, v77, v98
	v_lshlrev_b32_e32 v6, 11, v6
	v_mov_b32_e32 v7, v69
	v_lshl_add_u64 v[12:13], v[10:11], 0, v[6:7]
	ds_read_b128 v[6:9], v101
	s_waitcnt lgkmcnt(1)
	global_store_dwordx4 v[12:13], v[2:5], off sc0 sc1
	s_nop 1
	v_or_b32_e32 v2, v77, v100
	v_lshlrev_b32_e32 v2, 11, v2
	v_mov_b32_e32 v3, v69
	v_lshl_add_u64 v[2:3], v[10:11], 0, v[2:3]
	s_waitcnt lgkmcnt(0)
	global_store_dwordx4 v[2:3], v[6:9], off sc0 sc1
	ds_read_b128 v[2:5], v103
	s_nop 0
	v_or_b32_e32 v6, v77, v102
	v_lshlrev_b32_e32 v6, 11, v6
	v_mov_b32_e32 v7, v69
	v_lshl_add_u64 v[12:13], v[10:11], 0, v[6:7]
	ds_read_b128 v[6:9], v105
	s_waitcnt lgkmcnt(1)
	global_store_dwordx4 v[12:13], v[2:5], off sc0 sc1
	s_nop 1
	v_or_b32_e32 v2, v77, v104
	v_lshlrev_b32_e32 v2, 11, v2
	v_mov_b32_e32 v3, v69
	v_lshl_add_u64 v[2:3], v[10:11], 0, v[2:3]
	s_waitcnt lgkmcnt(0)
	global_store_dwordx4 v[2:3], v[6:9], off sc0 sc1
	ds_read_b128 v[2:5], v107
	s_nop 0
	v_or_b32_e32 v6, v77, v106
	v_lshlrev_b32_e32 v6, 11, v6
	v_mov_b32_e32 v7, v69
	v_lshl_add_u64 v[12:13], v[10:11], 0, v[6:7]
	ds_read_b128 v[6:9], v109
	s_waitcnt lgkmcnt(1)
	global_store_dwordx4 v[12:13], v[2:5], off sc0 sc1
	s_nop 1
	v_or_b32_e32 v2, v77, v108
	v_lshlrev_b32_e32 v2, 11, v2
	v_mov_b32_e32 v3, v69
	v_lshl_add_u64 v[2:3], v[10:11], 0, v[2:3]
	s_waitcnt lgkmcnt(0)
	global_store_dwordx4 v[2:3], v[6:9], off sc0 sc1
	s_waitcnt lgkmcnt(0)

; __device__ __forceinline__ unsigned pk2(float lo, float hi) { unsigned r; asm volatile("v_cvt_pk_bf16_f32 %0, %1, %2" : "=v"(r) : "v"(lo), "v"(hi)); return r; }
; __device__ __forceinline__ void p0_transpose_item(const float* W, int K, int N, const float* gain, const float* gain2  , bf16_t* WT, LAS unsigned* scr, int item, int lane) {
;     const int nblk = N / 64, kb = item / nblk, nb = item % nblk, k0 = 64 * kb, n0 = 64 * nb;
;     if (gain2 && k0 >= 1024) gain = gain2 - 1024;
;     const int n4 = lane & 15, kq = lane >> 4;
;     f32x4 r0[8], r1[8];
;     const float* src = W + (size_t)(k0 + 2 * kq) * N + n0 + 4 * n4;
; #pragma unroll
;     for (int j = 0; j < 8; ++j) { r0[j] = __builtin_nontemporal_load((const f32x4*)(src + (size_t)(8 * j) * N)); r1[j] = __builtin_nontemporal_load((const f32x4*)(src + (size_t)(8 * j + 1) * N)); }
; #pragma unroll
;     for (int j = 0; j < 8; ++j) {
;         float g0 = 1.f, g1 = 1.f; if (gain) { g0 = gain[k0 + 8 * j + 2 * kq]; g1 = gain[k0 + 8 * j + 2 * kq + 1]; }
; #pragma unroll
;         for (int i = 0; i < 4; ++i) scr[(4 * n4 + i) * 32 + (((j ^ (n4 & 7)) << 2) | kq)] = pk2(r0[j][i] * g0, r1[j][i] * g1);
.LBB0_142:
	s_andn2_saveexec_b64 s[28:29], s[28:29]
	s_cbranch_execz .LBB0_144
	v_add_u32_e32 v2, 0xeb00, v2
	v_lshlrev_b64 v[4:5], 26, v[76:77]
	v_readlane_b32 s40, v253, 18
	v_bfe_u32 v76, v2, 5, 11
	v_lshlrev_b32_e32 v2, 6, v3
	v_readlane_b32 s52, v253, 30
	v_readlane_b32 s53, v253, 31
	v_sub_u32_e32 v2, v110, v2
	v_and_b32_e32 v77, 0x7c0, v2
	v_lshl_add_u64 v[4:5], s[52:53], 0, v[4:5]
	v_lshl_or_b32 v2, v76, 19, v113
	v_mov_b32_e32 v3, v69
	v_lshl_add_u64 v[2:3], v[4:5], 0, v[2:3]
	v_lshlrev_b32_e32 v4, 2, v77
	v_mov_b32_e32 v5, v69
	v_lshl_add_u64 v[2:3], v[2:3], 0, v[4:5]
	v_lshl_add_u64 v[58:59], v[2:3], 0, v[68:69]
	v_add_co_u32_e32 v6, vcc, s37, v58
	s_mov_b32 s30, 0x72000
	s_nop 0
	v_addc_co_u32_e32 v7, vcc, 0, v59, vcc
	global_load_dwordx4 v[2:5], v[58:59], off nt
	s_nop 0
	global_load_dwordx4 v[6:9], v[6:7], off nt
	v_add_co_u32_e32 v10, vcc, s38, v58
	v_readlane_b32 s41, v253, 19
	s_nop 0
	v_addc_co_u32_e32 v11, vcc, 0, v59, vcc
	v_add_co_u32_e32 v14, vcc, s39, v58
	v_readlane_b32 s42, v253, 20
	s_nop 0
	v_addc_co_u32_e32 v15, vcc, 0, v59, vcc
	global_load_dwordx4 v[10:13], v[10:11], off nt
	s_nop 0
	global_load_dwordx4 v[14:17], v[14:15], off nt
	v_add_co_u32_e32 v18, vcc, s2, v58
	v_readlane_b32 s43, v253, 21
	s_nop 0
	v_addc_co_u32_e32 v19, vcc, 0, v59, vcc
	v_add_co_u32_e32 v22, vcc, s3, v58
	v_readlane_b32 s44, v253, 22
	s_nop 0
	v_addc_co_u32_e32 v23, vcc, 0, v59, vcc
	global_load_dwordx4 v[18:21], v[18:19], off nt
	s_nop 0
	global_load_dwordx4 v[22:25], v[22:23], off nt
	v_add_co_u32_e32 v26, vcc, s76, v58
	v_readlane_b32 s45, v253, 23
	s_nop 0
	v_addc_co_u32_e32 v27, vcc, 0, v59, vcc
	v_add_co_u32_e32 v30, vcc, s77, v58
	v_readlane_b32 s46, v253, 24
	s_nop 0
	v_addc_co_u32_e32 v31, vcc, 0, v59, vcc
	global_load_dwordx4 v[26:29], v[26:27], off nt
	s_waitcnt lgkmcnt(0)
	global_load_dwordx4 v[30:33], v[30:31], off nt
	v_add_co_u32_e32 v34, vcc, s78, v58
	v_readlane_b32 s47, v253, 25
	s_nop 0
	v_addc_co_u32_e32 v35, vcc, 0, v59, vcc
	v_add_co_u32_e32 v38, vcc, s79, v58
	v_readlane_b32 s48, v253, 26
	s_nop 0
	v_addc_co_u32_e32 v39, vcc, 0, v59, vcc
	global_load_dwordx4 v[34:37], v[34:35], off nt
	s_nop 0
	global_load_dwordx4 v[38:41], v[38:39], off nt
	v_add_co_u32_e32 v42, vcc, s80, v58
	v_readlane_b32 s49, v253, 27
	s_nop 0
	v_addc_co_u32_e32 v43, vcc, 0, v59, vcc
	v_add_co_u32_e32 v46, vcc, s81, v58
	v_readlane_b32 s50, v253, 28
	s_nop 0
	v_addc_co_u32_e32 v47, vcc, 0, v59, vcc
	global_load_dwordx4 v[42:45], v[42:43], off nt
	s_nop 0
	global_load_dwordx4 v[46:49], v[46:47], off nt
	v_add_co_u32_e32 v50, vcc, s82, v58
	v_readlane_b32 s51, v253, 29
	s_nop 0
	v_addc_co_u32_e32 v51, vcc, 0, v59, vcc
	v_add_co_u32_e32 v54, vcc, s83, v58
	v_readlane_b32 s54, v253, 32
	s_nop 0
	v_addc_co_u32_e32 v55, vcc, 0, v59, vcc
	global_load_dwordx4 v[50:53], v[50:51], off nt
	s_nop 0
	global_load_dwordx4 v[54:57], v[54:55], off nt
	v_add_co_u32_e32 v60, vcc, s84, v58
	v_readlane_b32 s55, v253, 33
	s_nop 0
	v_addc_co_u32_e32 v61, vcc, 0, v59, vcc
	v_add_co_u32_e32 v62, vcc, s30, v58
	s_nop 1
	v_addc_co_u32_e32 v63, vcc, 0, v59, vcc
	global_load_dwordx4 v[58:61], v[60:61], off nt
	s_nop 0
	global_load_dwordx4 v[62:65], v[62:63], off nt
	s_waitcnt vmcnt(14)
	v_cvt_pk_bf16_f32 v2, v2, v6
	v_add_u32_e32 v6, v71, v86
	ds_write_b32 v6, v2
	v_cvt_pk_bf16_f32 v2, v3, v7
	ds_write_b32 v6, v2 offset:128
	v_cvt_pk_bf16_f32 v2, v4, v8
	ds_write_b32 v6, v2 offset:256
	v_cvt_pk_bf16_f32 v2, v5, v9
	ds_write_b32 v6, v2 offset:384
	s_waitcnt vmcnt(12)
	v_cvt_pk_bf16_f32 v2, v10, v14
	v_add_u32_e32 v3, v87, v86
	ds_write_b32 v3, v2
	v_cvt_pk_bf16_f32 v2, v11, v15
	ds_write_b32 v3, v2 offset:128
	v_cvt_pk_bf16_f32 v2, v12, v16
	ds_write_b32 v3, v2 offset:256
	v_cvt_pk_bf16_f32 v2, v13, v17
	ds_write_b32 v3, v2 offset:384
	s_waitcnt vmcnt(10)
; #define LAS __attribute__((address_space(3)))
; __device__ __forceinline__ unsigned pk2(float lo, float hi) { unsigned r; asm volatile("v_cvt_pk_bf16_f32 %0, %1, %2" : "=v"(r) : "v"(lo), "v"(hi)); return r; }
; __device__ __forceinline__ void p0_transpose_item(const float* W, int K, int N, const float* gain, const float* gain2  , bf16_t* WT, LAS unsigned* scr, int item, int lane) {
;     ...
;     for (int j = 0; j < 8; ++j) {
;         float g0 = 1.f, g1 = 1.f; if (gain) { g0 = gain[k0 + 8 * j + 2 * kq]; g1 = gain[k0 + 8 * j + 2 * kq + 1]; }
; #pragma unroll
;         for (int i = 0; i < 4; ++i) scr[(4 * n4 + i) * 32 + (((j ^ (n4 & 7)) << 2) | kq)] = pk2(r0[j][i] * g0, r1[j][i] * g1);
;     }
;     asm volatile("s_waitcnt lgkmcnt(0)" ::: "memory");
; #pragma unroll
;     for (int it = 0; it < 8; ++it) {
;         const int n = (lane >> 3) + 8 * it, c = lane & 7;
;         const u32x4 v = *(const LAS u32x4*)(scr + n * 32 + ((c ^ ((n >> 2) & 7)) << 2));
;         *(u32x4*)(WT + (size_t)(n0 + n) * K + k0 + 8 * c) = v;
;     }
	v_cvt_pk_bf16_f32 v2, v18, v22
	v_add_u32_e32 v3, v88, v86
	ds_write_b32 v3, v2
	v_cvt_pk_bf16_f32 v2, v19, v23
	ds_write_b32 v3, v2 offset:128
	v_cvt_pk_bf16_f32 v2, v20, v24
	ds_write_b32 v3, v2 offset:256
	v_cvt_pk_bf16_f32 v2, v21, v25
	ds_write_b32 v3, v2 offset:384
	s_waitcnt vmcnt(8)
	v_cvt_pk_bf16_f32 v2, v26, v30
	v_add_u32_e32 v3, v89, v86
	ds_write_b32 v3, v2
	v_cvt_pk_bf16_f32 v2, v27, v31
	ds_write_b32 v3, v2 offset:128
	v_cvt_pk_bf16_f32 v2, v28, v32
	ds_write_b32 v3, v2 offset:256
	v_cvt_pk_bf16_f32 v2, v29, v33
	ds_write_b32 v3, v2 offset:384
	s_waitcnt vmcnt(6)
	v_cvt_pk_bf16_f32 v2, v34, v38
	v_add_u32_e32 v3, v90, v86
	ds_write_b32 v3, v2
	v_cvt_pk_bf16_f32 v2, v35, v39
	ds_write_b32 v3, v2 offset:128
	v_cvt_pk_bf16_f32 v2, v36, v40
	ds_write_b32 v3, v2 offset:256
	v_cvt_pk_bf16_f32 v2, v37, v41
	ds_write_b32 v3, v2 offset:384
	s_waitcnt vmcnt(4)
	v_cvt_pk_bf16_f32 v2, v42, v46
	v_add_u32_e32 v3, v91, v86
	ds_write_b32 v3, v2
	v_cvt_pk_bf16_f32 v2, v43, v47
	ds_write_b32 v3, v2 offset:128
	v_cvt_pk_bf16_f32 v2, v44, v48
	ds_write_b32 v3, v2 offset:256
	v_cvt_pk_bf16_f32 v2, v45, v49
	ds_write_b32 v3, v2 offset:384
	s_waitcnt vmcnt(2)
	v_cvt_pk_bf16_f32 v2, v50, v54
	v_add_u32_e32 v3, v92, v86
	ds_write_b32 v3, v2
	v_cvt_pk_bf16_f32 v2, v51, v55
	ds_write_b32 v3, v2 offset:128
	v_cvt_pk_bf16_f32 v2, v52, v56
	ds_write_b32 v3, v2 offset:256
	v_cvt_pk_bf16_f32 v2, v53, v57
	ds_write_b32 v3, v2 offset:384
	s_waitcnt vmcnt(0)
	v_cvt_pk_bf16_f32 v2, v58, v62
	v_add_u32_e32 v3, v93, v86
	ds_write_b32 v3, v2
	v_cvt_pk_bf16_f32 v2, v59, v63
	ds_write_b32 v3, v2 offset:128
	v_cvt_pk_bf16_f32 v2, v60, v64
	ds_write_b32 v3, v2 offset:256
	v_cvt_pk_bf16_f32 v2, v61, v65
	ds_write_b32 v3, v2 offset:384
	v_lshlrev_b32_e32 v2, 7, v76
	v_mov_b32_e32 v3, v69
	v_lshl_add_u64 v[2:3], v[74:75], 0, v[2:3]
	v_lshlrev_b32_e32 v4, 1, v70
	v_mov_b32_e32 v5, v69
	s_waitcnt lgkmcnt(0)
	v_lshl_add_u64 v[2:3], v[2:3], 0, v[4:5]
	v_lshl_add_u64 v[10:11], v[2:3], 0, s[22:23]
	ds_read_b128 v[2:5], v95
	v_or_b32_e32 v6, v77, v94
	v_lshlrev_b32_e32 v6, 14, v6
	v_mov_b32_e32 v7, v69
	v_lshl_add_u64 v[12:13], v[10:11], 0, v[6:7]
	ds_read_b128 v[6:9], v97
	s_waitcnt lgkmcnt(1)
	global_store_dwordx4 v[12:13], v[2:5], off sc0 sc1
	s_nop 1
	v_or_b32_e32 v2, v77, v96
	v_lshlrev_b32_e32 v2, 14, v2
	v_mov_b32_e32 v3, v69
	v_lshl_add_u64 v[2:3], v[10:11], 0, v[2:3]
	s_waitcnt lgkmcnt(0)
	global_store_dwordx4 v[2:3], v[6:9], off sc0 sc1
	ds_read_b128 v[2:5], v99
	s_nop 0
	v_or_b32_e32 v6, v77, v98
	v_lshlrev_b32_e32 v6, 14, v6
	v_mov_b32_e32 v7, v69
	v_lshl_add_u64 v[12:13], v[10:11], 0, v[6:7]
	ds_read_b128 v[6:9], v101
	s_waitcnt lgkmcnt(1)
	global_store_dwordx4 v[12:13], v[2:5], off sc0 sc1
	s_nop 1
	v_or_b32_e32 v2, v77, v100
	v_lshlrev_b32_e32 v2, 14, v2
	v_mov_b32_e32 v3, v69
	v_lshl_add_u64 v[2:3], v[10:11], 0, v[2:3]
	s_waitcnt lgkmcnt(0)
	global_store_dwordx4 v[2:3], v[6:9], off sc0 sc1
	ds_read_b128 v[2:5], v103
	s_nop 0
	v_or_b32_e32 v6, v77, v102
	v_lshlrev_b32_e32 v6, 14, v6
	v_mov_b32_e32 v7, v69
	v_lshl_add_u64 v[12:13], v[10:11], 0, v[6:7]
	ds_read_b128 v[6:9], v105
	s_waitcnt lgkmcnt(1)
	global_store_dwordx4 v[12:13], v[2:5], off sc0 sc1
	s_nop 1
	v_or_b32_e32 v2, v77, v104
	v_lshlrev_b32_e32 v2, 14, v2
	v_mov_b32_e32 v3, v69
	v_lshl_add_u64 v[2:3], v[10:11], 0, v[2:3]
	s_waitcnt lgkmcnt(0)
	global_store_dwordx4 v[2:3], v[6:9], off sc0 sc1
	ds_read_b128 v[2:5], v107
	s_nop 0
	v_or_b32_e32 v6, v77, v106
	v_lshlrev_b32_e32 v6, 14, v6
	v_mov_b32_e32 v7, v69
	v_lshl_add_u64 v[12:13], v[10:11], 0, v[6:7]
	ds_read_b128 v[6:9], v109
	s_waitcnt lgkmcnt(1)
	global_store_dwordx4 v[12:13], v[2:5], off sc0 sc1
	s_nop 1
	v_or_b32_e32 v2, v77, v108
	v_lshlrev_b32_e32 v2, 14, v2
	v_mov_b32_e32 v3, v69
	v_lshl_add_u64 v[2:3], v[10:11], 0, v[2:3]
	s_waitcnt lgkmcnt(0)
	global_store_dwordx4 v[2:3], v[6:9], off sc0 sc1
	s_waitcnt lgkmcnt(0)

; #define LAS __attribute__((address_space(3)))
; __device__ __forceinline__ unsigned pk2(float lo, float hi) { unsigned r; asm volatile("v_cvt_pk_bf16_f32 %0, %1, %2" : "=v"(r) : "v"(lo), "v"(hi)); return r; }
; __device__ __forceinline__ void p0_transpose_item(const float* W, int K, int N, const float* gain, const float* gain2  , bf16_t* WT, LAS unsigned* scr, int item, int lane) {
;     ...
;     for (int j = 0; j < 8; ++j) {
;         float g0 = 1.f, g1 = 1.f; if (gain) { g0 = gain[k0 + 8 * j + 2 * kq]; g1 = gain[k0 + 8 * j + 2 * kq + 1]; }
; #pragma unroll
;         for (int i = 0; i < 4; ++i) scr[(4 * n4 + i) * 32 + (((j ^ (n4 & 7)) << 2) | kq)] = pk2(r0[j][i] * g0, r1[j][i] * g1);
;     }
;     asm volatile("s_waitcnt lgkmcnt(0)" ::: "memory");
; #pragma unroll
;     for (int it = 0; it < 8; ++it) {
;         const int n = (lane >> 3) + 8 * it, c = lane & 7;
;         const u32x4 v = *(const LAS u32x4*)(scr + n * 32 + ((c ^ ((n >> 2) & 7)) << 2));
;         *(u32x4*)(WT + (size_t)(n0 + n) * K + k0 + 8 * c) = v;
;     }
.LBB0_162:
	s_waitcnt vmcnt(0)
	v_mul_f32_e32 v2, v2, v18
	v_mul_f32_e32 v6, v6, v19
	v_cvt_pk_bf16_f32 v2, v2, v6
	v_add_u32_e32 v6, v93, v86
	ds_write_b32 v6, v2
	v_mul_f32_e32 v2, v3, v18
	v_mul_f32_e32 v3, v7, v19
	v_cvt_pk_bf16_f32 v2, v2, v3
	ds_write_b32 v6, v2 offset:128
	v_mul_f32_e32 v2, v4, v18
	v_mul_f32_e32 v3, v8, v19
	v_cvt_pk_bf16_f32 v2, v2, v3
	ds_write_b32 v6, v2 offset:256
	v_mul_f32_e32 v2, v5, v18
	v_mul_f32_e32 v3, v9, v19
	v_cvt_pk_bf16_f32 v2, v2, v3
	ds_write_b32 v6, v2 offset:384
	v_lshlrev_b32_e32 v2, 1, v85
	v_mov_b32_e32 v3, v69
	v_lshl_add_u64 v[2:3], v[74:75], 0, v[2:3]
	v_lshlrev_b32_e32 v4, 1, v70
	v_mov_b32_e32 v5, v69
	s_waitcnt lgkmcnt(0)
	v_lshl_add_u64 v[2:3], v[2:3], 0, v[4:5]
	v_lshl_add_u64 v[10:11], v[2:3], 0, s[24:25]
	ds_read_b128 v[2:5], v95
	v_or_b32_e32 v6, v84, v94
	v_lshlrev_b32_e32 v6, 12, v6
	v_mov_b32_e32 v7, v69
	v_lshl_add_u64 v[12:13], v[10:11], 0, v[6:7]
	ds_read_b128 v[6:9], v97
	s_waitcnt lgkmcnt(1)
	global_store_dwordx4 v[12:13], v[2:5], off sc0 sc1
	s_nop 1
	v_or_b32_e32 v2, v84, v96
	v_lshlrev_b32_e32 v2, 12, v2
	v_mov_b32_e32 v3, v69
	v_lshl_add_u64 v[2:3], v[10:11], 0, v[2:3]
	s_waitcnt lgkmcnt(0)
	global_store_dwordx4 v[2:3], v[6:9], off sc0 sc1
	ds_read_b128 v[2:5], v99
	s_nop 0
	v_or_b32_e32 v6, v84, v98
	v_lshlrev_b32_e32 v6, 12, v6
	v_mov_b32_e32 v7, v69
	v_lshl_add_u64 v[12:13], v[10:11], 0, v[6:7]
	ds_read_b128 v[6:9], v101
	s_waitcnt lgkmcnt(1)
	global_store_dwordx4 v[12:13], v[2:5], off sc0 sc1
	s_nop 1
	v_or_b32_e32 v2, v84, v100
	v_lshlrev_b32_e32 v2, 12, v2
	v_mov_b32_e32 v3, v69
	v_lshl_add_u64 v[2:3], v[10:11], 0, v[2:3]
	s_waitcnt lgkmcnt(0)
	global_store_dwordx4 v[2:3], v[6:9], off sc0 sc1
	ds_read_b128 v[2:5], v103
	s_nop 0
	v_or_b32_e32 v6, v84, v102
	v_lshlrev_b32_e32 v6, 12, v6
	v_mov_b32_e32 v7, v69
	v_lshl_add_u64 v[12:13], v[10:11], 0, v[6:7]
	ds_read_b128 v[6:9], v105
	s_waitcnt lgkmcnt(1)
	global_store_dwordx4 v[12:13], v[2:5], off sc0 sc1
	s_nop 1
	v_or_b32_e32 v2, v84, v104
	v_lshlrev_b32_e32 v2, 12, v2
	v_mov_b32_e32 v3, v69
	v_lshl_add_u64 v[2:3], v[10:11], 0, v[2:3]
	s_waitcnt lgkmcnt(0)
	global_store_dwordx4 v[2:3], v[6:9], off sc0 sc1
	ds_read_b128 v[2:5], v107
	s_nop 0
	v_or_b32_e32 v6, v84, v106
	v_lshlrev_b32_e32 v6, 12, v6
	v_mov_b32_e32 v7, v69
	v_lshl_add_u64 v[12:13], v[10:11], 0, v[6:7]
	ds_read_b128 v[6:9], v109
	s_waitcnt lgkmcnt(1)
	global_store_dwordx4 v[12:13], v[2:5], off sc0 sc1
	s_nop 1
	v_or_b32_e32 v2, v84, v108
	v_lshlrev_b32_e32 v2, 12, v2
	v_mov_b32_e32 v3, v69
	v_lshl_add_u64 v[2:3], v[10:11], 0, v[2:3]
	s_waitcnt lgkmcnt(0)
	global_store_dwordx4 v[2:3], v[6:9], off sc0 sc1
	s_waitcnt lgkmcnt(0)

; __device__ __forceinline__ u32x4 pack8(f32x4 a, f32x4 b) { u32x4 w; w.x = pk2(a[0], a[1]); w.y = pk2(a[2], a[3]); w.z = pk2(b[0], b[1]); w.w = pk2(b[2], b[3]); return w; }
;     __device__ __forceinline__ void operator()(const f32x4 (&acc)[2][2][4][2], const Unit& un, int wr, int wc, int fr, int fq, int lane) const {
;         const int c0 = un.pn * 128 + wc * 32 + 8 * fq;
;         const f32x4 bv0 = *(const f32x4*)(bias + c0), bv1 = *(const f32x4*)(bias + c0 + 4);
; #pragma unroll
;         for (int ai = 0; ai < 2; ++ai)
; #pragma unroll
;             for (int m = 0; m < 4; ++m) {
;                 const int row = un.pm * 256 + ai * 128 + wr * 64 + m * 16 + fr; float ss = 0.f;
;                 const size_t off = (size_t)row * 1024 + c0, offs = (size_t)row * 2048 + 1024 + c0;
;                 const u32x4 gw = *(const u32x4*)(gb + off);
;                 const f32x4 g0 = (f32x4){bflo(gw.x), bfhi(gw.x), bflo(gw.y), bfhi(gw.y)}, g1 = (f32x4){bflo(gw.z), bfhi(gw.z), bflo(gw.w), bfhi(gw.w)};
;                 const f32x4 z0 = acc[ai][0][m][0] + bv0, z1 = acc[ai][0][m][1] + bv1;
;                 f32x4 o0, o1;
; #pragma unroll
;                 for (int j = 0; j < 4; ++j) { o0[j] = g0[j] * __builtin_amdgcn_rcpf(1.f + __expf(-z0[j])); o1[j] = g1[j] * __builtin_amdgcn_rcpf(1.f + __expf(-z1[j])); ss += o0[j] * o0[j] + o1[j] * o1[j]; }
;                 *(u32x4*)(s + offs) = pack8(o0, o1);
;                 ss += __shfl_xor(ss, 16); ss += __shfl_xor(ss, 32);
;                 if (fq == 0) ssqs[(size_t)row * 32 + un.pn * 4 + wc] = ss;
.LBB0_1062:
	v_lshl_or_b32 v84, s48, 7, v90
	v_ashrrev_i32_e32 v85, 31, v84
	v_lshl_add_u64 v[30:31], v[84:85], 2, s[20:21]
	global_load_dwordx4 v[26:29], v[30:31], off offset:16
	s_nop 0
	global_load_dwordx4 v[30:33], v[30:31], off
	v_lshl_add_u32 v86, s30, 8, v88
	v_ashrrev_i32_e32 v87, 31, v86
	v_lshlrev_b64 v[92:93], 11, v[86:87]
	v_lshl_add_u64 v[92:93], s[0:1], 0, v[92:93]
	v_lshlrev_b64 v[84:85], 1, v[84:85]
	v_lshl_add_u64 v[92:93], v[92:93], 0, v[84:85]
	v_add_co_u32_e32 v128, vcc, 0x8000, v92
	s_nop 1
	v_addc_co_u32_e32 v129, vcc, 0, v93, vcc
	global_load_dwordx4 v[100:103], v[128:129], off
	v_add_co_u32_e32 v128, vcc, 0x8000, v128
	s_nop 1
	v_addc_co_u32_e32 v129, vcc, 0, v129, vcc
	global_load_dwordx4 v[104:107], v[128:129], off
	v_add_co_u32_e32 v128, vcc, 0x8000, v128
	s_nop 1
	v_addc_co_u32_e32 v129, vcc, 0, v129, vcc
	global_load_dwordx4 v[108:111], v[128:129], off
	v_add_co_u32_e32 v128, vcc, 0x28000, v128
	s_nop 1
	v_addc_co_u32_e32 v129, vcc, 0, v129, vcc
	global_load_dwordx4 v[112:115], v[128:129], off
	v_add_co_u32_e32 v128, vcc, 0x8000, v128
	s_nop 1
	v_addc_co_u32_e32 v129, vcc, 0, v129, vcc
	global_load_dwordx4 v[116:119], v[128:129], off
	v_add_co_u32_e32 v128, vcc, 0x8000, v128
	s_nop 1
	v_addc_co_u32_e32 v129, vcc, 0, v129, vcc
	global_load_dwordx4 v[120:123], v[128:129], off
	v_add_co_u32_e32 v128, vcc, 0x8000, v128
	s_nop 1
	v_addc_co_u32_e32 v129, vcc, 0, v129, vcc
	global_load_dwordx4 v[124:127], v[128:129], off
	global_load_dwordx4 v[92:95], v[92:93], off
	s_lshl_b32 s48, s48, 2
	s_ashr_i32 s49, s48, 31
	s_waitcnt vmcnt(0)
	v_add_f32_e32 v66, v66, v26
	v_add_f32_e32 v70, v70, v30
	v_add_f32_e32 v71, v71, v31
	v_add_f32_e32 v67, v67, v27
	v_mul_f32_e32 v70, 0xbfb8aa3b, v70
	v_mul_f32_e32 v66, 0xbfb8aa3b, v66
	v_mul_f32_e32 v71, 0xbfb8aa3b, v71
	v_mul_f32_e32 v67, 0xbfb8aa3b, v67
	v_exp_f32_e32 v70, v70
	v_exp_f32_e32 v66, v66
	v_exp_f32_e32 v71, v71
	v_exp_f32_e32 v67, v67
	v_add_f32_e32 v70, 1.0, v70
	v_add_f32_e32 v66, 1.0, v66
	v_add_f32_e32 v71, 1.0, v71
	v_add_f32_e32 v67, 1.0, v67
	v_rcp_f32_e32 v70, v70
	v_rcp_f32_e32 v66, v66
	v_rcp_f32_e32 v71, v71
	v_rcp_f32_e32 v67, v67
	v_lshlrev_b32_e32 v96, 16, v92
	v_and_b32_e32 v92, 0xffff0000, v92
	v_lshlrev_b32_e32 v98, 16, v94
	v_and_b32_e32 v94, 0xffff0000, v94
	v_mul_f32_e32 v70, v70, v96
	v_mul_f32_e32 v96, v66, v98
	v_mul_f32_e32 v71, v71, v92
	v_mul_f32_e32 v92, v67, v94
	v_mul_f32_e32 v66, v96, v96
	v_mul_f32_e32 v67, v92, v92
	v_fmac_f32_e32 v66, v70, v70
	v_fmac_f32_e32 v67, v71, v71
	v_add_f32_e32 v68, v68, v28
	v_add_f32_e32 v66, v66, v67
	v_add_f32_e32 v67, v72, v32
	v_mul_f32_e32 v68, 0xbfb8aa3b, v68
	v_mul_f32_e32 v67, 0xbfb8aa3b, v67
	v_exp_f32_e32 v68, v68
	v_exp_f32_e32 v67, v67
	v_lshlrev_b32_e32 v99, 16, v95
	v_lshlrev_b32_e32 v97, 16, v93
	v_add_f32_e32 v68, 1.0, v68
	v_add_f32_e32 v67, 1.0, v67
	v_rcp_f32_e32 v68, v68
	v_rcp_f32_e32 v67, v67
	v_add_f32_e32 v69, v69, v29
	v_mul_f32_e32 v69, 0xbfb8aa3b, v69
	v_mul_f32_e32 v72, v68, v99
	v_mul_f32_e32 v67, v67, v97
	v_mul_f32_e32 v68, v72, v72
	v_fmac_f32_e32 v68, v67, v67
	v_add_f32_e32 v66, v68, v66
	v_add_f32_e32 v68, v73, v33
	v_mul_f32_e32 v68, 0xbfb8aa3b, v68
	v_exp_f32_e32 v69, v69
	v_exp_f32_e32 v68, v68
	v_and_b32_e32 v95, 0xffff0000, v95
	v_and_b32_e32 v93, 0xffff0000, v93
	v_add_f32_e32 v69, 1.0, v69
	v_add_f32_e32 v68, 1.0, v68
	v_rcp_f32_e32 v69, v69
	v_rcp_f32_e32 v68, v68
	v_mul_f32_e32 v69, v69, v95
	v_mul_f32_e32 v68, v68, v93
	v_mul_f32_e32 v73, v69, v69
	v_fmac_f32_e32 v73, v68, v68
	v_add_f32_e32 v73, v73, v66
	v_cvt_pk_bf16_f32 v66, v70, v71
	v_lshlrev_b64 v[70:71], 12, v[86:87]
	v_lshl_add_u64 v[70:71], s[22:23], 0, v[70:71]
	v_cvt_pk_bf16_f32 v67, v67, v68
	v_lshl_add_u64 v[70:71], v[70:71], 0, v[84:85]
	v_cvt_pk_bf16_f32 v68, v96, v92
	v_cvt_pk_bf16_f32 v69, v72, v69
	global_store_dwordx4 v[70:71], v[66:69], off offset:2048 sc0 sc1
	s_nop 1
	v_and_b32_e32 v67, 64, v218
	v_xor_b32_e32 v66, 16, v218
	v_add_u32_e32 v67, 64, v67
	v_cmp_lt_i32_e32 vcc, v66, v67
	v_xor_b32_e32 v69, 32, v218
	s_nop 0
	v_cndmask_b32_e32 v66, v218, v66, vcc
	v_lshlrev_b32_e32 v68, 2, v66
	ds_bpermute_b32 v66, v68, v73
	v_cmp_lt_i32_e32 vcc, v69, v67
	s_waitcnt lgkmcnt(0)
	v_add_f32_e32 v66, v73, v66
	v_cndmask_b32_e32 v67, v218, v69, vcc
	v_lshlrev_b32_e32 v69, 2, v67
	ds_bpermute_b32 v67, v69, v66
	s_and_saveexec_b64 s[30:31], s[36:37]
	s_cbranch_execz .LBB0_1064
	v_lshlrev_b64 v[70:71], 7, v[86:87]
	v_lshl_add_u64 v[70:71], s[24:25], 0, v[70:71]
	v_lshl_add_u64 v[70:71], s[48:49], 2, v[70:71]
	s_lshl_b32 s74, s64, 2
	v_lshl_add_u64 v[70:71], v[70:71], 0, s[74:75]
	s_waitcnt lgkmcnt(0)
	v_add_f32_e32 v66, v66, v67
	global_store_dword v[70:71], v66, off
; __device__ __forceinline__ u32x4 pack8(f32x4 a, f32x4 b) { u32x4 w; w.x = pk2(a[0], a[1]); w.y = pk2(a[2], a[3]); w.z = pk2(b[0], b[1]); w.w = pk2(b[2], b[3]); return w; }
;     __device__ __forceinline__ void operator()(const f32x4 (&acc)[2][2][4][2], const Unit& un, int wr, int wc, int fr, int fq, int lane) const {
;     ...
;         for (int ai = 0; ai < 2; ++ai)
; #pragma unroll
;             for (int m = 0; m < 4; ++m) {
;                 const int row = un.pm * 256 + ai * 128 + wr * 64 + m * 16 + fr; float ss = 0.f;
;                 const size_t off = (size_t)row * 1024 + c0, offs = (size_t)row * 2048 + 1024 + c0;
;                 const u32x4 gw = *(const u32x4*)(gb + off);
;                 const f32x4 g0 = (f32x4){bflo(gw.x), bfhi(gw.x), bflo(gw.y), bfhi(gw.y)}, g1 = (f32x4){bflo(gw.z), bfhi(gw.z), bflo(gw.w), bfhi(gw.w)};
;                 const f32x4 z0 = acc[ai][0][m][0] + bv0, z1 = acc[ai][0][m][1] + bv1;
;                 f32x4 o0, o1;
; #pragma unroll
;                 for (int j = 0; j < 4; ++j) { o0[j] = g0[j] * __builtin_amdgcn_rcpf(1.f + __expf(-z0[j])); o1[j] = g1[j] * __builtin_amdgcn_rcpf(1.f + __expf(-z1[j])); ss += o0[j] * o0[j] + o1[j] * o1[j]; }
;                 *(u32x4*)(s + offs) = pack8(o0, o1);
;                 ss += __shfl_xor(ss, 16); ss += __shfl_xor(ss, 32);
;                 if (fq == 0) ssqs[(size_t)row * 32 + un.pn * 4 + wc] = ss;
.LBB0_1064:
	s_or_b64 exec, exec, s[30:31]
	v_or_b32_e32 v66, 16, v86
	s_waitcnt lgkmcnt(0)
	v_ashrrev_i32_e32 v67, 31, v66
	v_lshlrev_b64 v[70:71], 11, v[66:67]
	v_lshl_add_u64 v[70:71], s[0:1], 0, v[70:71]
	v_lshl_add_u64 v[70:71], v[70:71], 0, v[84:85]
	v_add_f32_e32 v58, v58, v26
	v_add_f32_e32 v59, v59, v27
	v_add_f32_e32 v62, v62, v30
	v_add_f32_e32 v63, v63, v31
	v_add_f32_e32 v60, v60, v28
	v_add_f32_e32 v65, v65, v33
	v_add_f32_e32 v61, v61, v29
	v_mul_f32_e32 v58, 0xbfb8aa3b, v58
	v_mul_f32_e32 v59, 0xbfb8aa3b, v59
	v_add_f32_e32 v64, v64, v32
	v_mul_f32_e32 v62, 0xbfb8aa3b, v62
	v_mul_f32_e32 v63, 0xbfb8aa3b, v63
	v_mul_f32_e32 v60, 0xbfb8aa3b, v60
	v_mul_f32_e32 v65, 0xbfb8aa3b, v65
	v_mul_f32_e32 v61, 0xbfb8aa3b, v61
	v_exp_f32_e32 v58, v58
	v_exp_f32_e32 v59, v59
	v_mul_f32_e32 v64, 0xbfb8aa3b, v64
	v_exp_f32_e32 v62, v62
	v_exp_f32_e32 v63, v63
	v_exp_f32_e32 v60, v60
	v_exp_f32_e32 v65, v65
	v_exp_f32_e32 v61, v61
	v_exp_f32_e32 v64, v64
	v_add_f32_e32 v58, 1.0, v58
	v_add_f32_e32 v59, 1.0, v59
	v_add_f32_e32 v62, 1.0, v62
	v_add_f32_e32 v63, 1.0, v63
	v_add_f32_e32 v60, 1.0, v60
	v_add_f32_e32 v65, 1.0, v65
	v_add_f32_e32 v61, 1.0, v61
	v_rcp_f32_e32 v58, v58
	v_rcp_f32_e32 v59, v59
	v_add_f32_e32 v64, 1.0, v64
	v_rcp_f32_e32 v62, v62
	v_rcp_f32_e32 v63, v63
	v_rcp_f32_e32 v60, v60
	v_rcp_f32_e32 v65, v65
	v_rcp_f32_e32 v61, v61
	v_rcp_f32_e32 v64, v64
	v_lshlrev_b32_e32 v93, 16, v102
	v_and_b32_e32 v72, 0xffff0000, v102
	v_lshlrev_b32_e32 v87, 16, v100
	v_and_b32_e32 v70, 0xffff0000, v100
	v_lshlrev_b32_e32 v92, 16, v101
	v_and_b32_e32 v71, 0xffff0000, v101
	v_lshlrev_b32_e32 v94, 16, v103
	v_and_b32_e32 v73, 0xffff0000, v103
	v_mul_f32_e32 v58, v58, v93
	v_mul_f32_e32 v59, v59, v72
	v_mul_f32_e32 v62, v62, v87
	v_mul_f32_e32 v63, v63, v70
	v_mul_f32_e32 v70, v60, v94
	v_mul_f32_e32 v65, v65, v71
	v_mul_f32_e32 v71, v61, v73
	v_mul_f32_e32 v60, v58, v58
	v_mul_f32_e32 v61, v59, v59
	v_mul_f32_e32 v64, v64, v92
	v_mul_f32_e32 v72, v70, v70
	v_fmac_f32_e32 v60, v62, v62
	v_fmac_f32_e32 v61, v63, v63
	v_mul_f32_e32 v73, v71, v71
	v_fmac_f32_e32 v72, v64, v64
	v_add_f32_e32 v60, v60, v61
	v_add_f32_e32 v60, v72, v60
	v_fmac_f32_e32 v73, v65, v65
	v_add_f32_e32 v72, v73, v60
	ds_bpermute_b32 v73, v68, v72
	v_cvt_pk_bf16_f32 v60, v62, v63
	v_cvt_pk_bf16_f32 v61, v64, v65
	v_cvt_pk_bf16_f32 v62, v58, v59
	v_lshlrev_b64 v[64:65], 12, v[66:67]
	s_waitcnt lgkmcnt(0)
	v_add_f32_e32 v58, v72, v73
	ds_bpermute_b32 v59, v69, v58
	v_lshl_add_u64 v[64:65], s[22:23], 0, v[64:65]
	v_lshl_add_u64 v[64:65], v[64:65], 0, v[84:85]
	v_cvt_pk_bf16_f32 v63, v70, v71
	global_store_dwordx4 v[64:65], v[60:63], off offset:2048 sc0 sc1
	s_and_saveexec_b64 s[30:31], s[36:37]
	s_cbranch_execz .LBB0_1066
	v_lshlrev_b64 v[60:61], 7, v[66:67]
	v_lshl_add_u64 v[60:61], s[24:25], 0, v[60:61]
	v_lshl_add_u64 v[60:61], s[48:49], 2, v[60:61]
	s_lshl_b32 s74, s64, 2
	v_lshl_add_u64 v[60:61], v[60:61], 0, s[74:75]
	s_waitcnt lgkmcnt(0)
	v_add_f32_e32 v58, v58, v59
	global_store_dword v[60:61], v58, off
.LBB0_1066:
	s_or_b64 exec, exec, s[30:31]
	v_or_b32_e32 v58, 32, v86
	s_waitcnt lgkmcnt(0)
	v_ashrrev_i32_e32 v59, 31, v58
	v_lshlrev_b64 v[60:61], 11, v[58:59]
	v_lshl_add_u64 v[60:61], s[0:1], 0, v[60:61]
	v_lshl_add_u64 v[60:61], v[60:61], 0, v[84:85]
	v_add_f32_e32 v50, v50, v26
	v_add_f32_e32 v51, v51, v27
	v_add_f32_e32 v54, v54, v30
	v_add_f32_e32 v55, v55, v31
	v_add_f32_e32 v52, v52, v28
	v_add_f32_e32 v57, v57, v33
	v_add_f32_e32 v53, v53, v29
	v_mul_f32_e32 v50, 0xbfb8aa3b, v50
	v_mul_f32_e32 v51, 0xbfb8aa3b, v51
	v_add_f32_e32 v56, v56, v32
	v_mul_f32_e32 v54, 0xbfb8aa3b, v54
	v_mul_f32_e32 v55, 0xbfb8aa3b, v55
	v_mul_f32_e32 v52, 0xbfb8aa3b, v52
	v_mul_f32_e32 v57, 0xbfb8aa3b, v57
	v_mul_f32_e32 v53, 0xbfb8aa3b, v53
	v_exp_f32_e32 v50, v50
	v_exp_f32_e32 v51, v51
	v_mul_f32_e32 v56, 0xbfb8aa3b, v56
	v_exp_f32_e32 v54, v54
	v_exp_f32_e32 v55, v55
	v_exp_f32_e32 v52, v52
	v_exp_f32_e32 v57, v57
	v_exp_f32_e32 v53, v53
	v_exp_f32_e32 v56, v56
	v_add_f32_e32 v50, 1.0, v50
	v_add_f32_e32 v51, 1.0, v51
	v_add_f32_e32 v54, 1.0, v54
	v_add_f32_e32 v55, 1.0, v55
	v_add_f32_e32 v52, 1.0, v52
	v_add_f32_e32 v57, 1.0, v57
	v_add_f32_e32 v53, 1.0, v53
	v_rcp_f32_e32 v50, v50
	v_rcp_f32_e32 v51, v51
	v_add_f32_e32 v56, 1.0, v56
	v_rcp_f32_e32 v54, v54
	v_rcp_f32_e32 v55, v55
	v_rcp_f32_e32 v52, v52
	v_rcp_f32_e32 v57, v57
	v_rcp_f32_e32 v53, v53
	v_rcp_f32_e32 v56, v56
	v_lshlrev_b32_e32 v66, 16, v106
	v_and_b32_e32 v62, 0xffff0000, v106
	v_lshlrev_b32_e32 v64, 16, v104
	v_and_b32_e32 v60, 0xffff0000, v104
	v_lshlrev_b32_e32 v65, 16, v105
	v_and_b32_e32 v61, 0xffff0000, v105
	v_lshlrev_b32_e32 v67, 16, v107
	v_and_b32_e32 v63, 0xffff0000, v107
	v_mul_f32_e32 v50, v50, v66
	v_mul_f32_e32 v51, v51, v62
	v_mul_f32_e32 v54, v54, v64
	v_mul_f32_e32 v55, v55, v60
	v_mul_f32_e32 v60, v52, v67
	v_mul_f32_e32 v57, v57, v61
	v_mul_f32_e32 v61, v53, v63
	v_mul_f32_e32 v52, v50, v50
	v_mul_f32_e32 v53, v51, v51
	v_mul_f32_e32 v56, v56, v65
	v_mul_f32_e32 v62, v60, v60
	v_fmac_f32_e32 v52, v54, v54
	v_fmac_f32_e32 v53, v55, v55
	v_mul_f32_e32 v63, v61, v61
	v_fmac_f32_e32 v62, v56, v56
	v_add_f32_e32 v52, v52, v53
	v_add_f32_e32 v52, v62, v52
	v_fmac_f32_e32 v63, v57, v57
	v_add_f32_e32 v62, v63, v52
	ds_bpermute_b32 v63, v68, v62
	v_cvt_pk_bf16_f32 v52, v54, v55
	v_cvt_pk_bf16_f32 v53, v56, v57
	v_cvt_pk_bf16_f32 v54, v50, v51
	v_lshlrev_b64 v[56:57], 12, v[58:59]
	s_waitcnt lgkmcnt(0)
	v_add_f32_e32 v50, v62, v63
	ds_bpermute_b32 v51, v69, v50
	v_lshl_add_u64 v[56:57], s[22:23], 0, v[56:57]
	v_lshl_add_u64 v[56:57], v[56:57], 0, v[84:85]
	v_cvt_pk_bf16_f32 v55, v60, v61
	global_store_dwordx4 v[56:57], v[52:55], off offset:2048 sc0 sc1
	s_and_saveexec_b64 s[30:31], s[36:37]
	s_cbranch_execz .LBB0_1068
	v_lshlrev_b64 v[52:53], 7, v[58:59]
	v_lshl_add_u64 v[52:53], s[24:25], 0, v[52:53]
	v_lshl_add_u64 v[52:53], s[48:49], 2, v[52:53]
	s_lshl_b32 s74, s64, 2
	v_lshl_add_u64 v[52:53], v[52:53], 0, s[74:75]
	s_waitcnt lgkmcnt(0)
	v_add_f32_e32 v50, v50, v51
	global_store_dword v[52:53], v50, off
; __device__ __forceinline__ u32x4 pack8(f32x4 a, f32x4 b) { u32x4 w; w.x = pk2(a[0], a[1]); w.y = pk2(a[2], a[3]); w.z = pk2(b[0], b[1]); w.w = pk2(b[2], b[3]); return w; }
;     __device__ __forceinline__ void operator()(const f32x4 (&acc)[2][2][4][2], const Unit& un, int wr, int wc, int fr, int fq, int lane) const {
;     ...
;         for (int ai = 0; ai < 2; ++ai)
; #pragma unroll
;             for (int m = 0; m < 4; ++m) {
;                 const int row = un.pm * 256 + ai * 128 + wr * 64 + m * 16 + fr; float ss = 0.f;
;                 const size_t off = (size_t)row * 1024 + c0, offs = (size_t)row * 2048 + 1024 + c0;
;                 const u32x4 gw = *(const u32x4*)(gb + off);
;                 const f32x4 g0 = (f32x4){bflo(gw.x), bfhi(gw.x), bflo(gw.y), bfhi(gw.y)}, g1 = (f32x4){bflo(gw.z), bfhi(gw.z), bflo(gw.w), bfhi(gw.w)};
;                 const f32x4 z0 = acc[ai][0][m][0] + bv0, z1 = acc[ai][0][m][1] + bv1;
;                 f32x4 o0, o1;
; #pragma unroll
;                 for (int j = 0; j < 4; ++j) { o0[j] = g0[j] * __builtin_amdgcn_rcpf(1.f + __expf(-z0[j])); o1[j] = g1[j] * __builtin_amdgcn_rcpf(1.f + __expf(-z1[j])); ss += o0[j] * o0[j] + o1[j] * o1[j]; }
;                 *(u32x4*)(s + offs) = pack8(o0, o1);
;                 ss += __shfl_xor(ss, 16); ss += __shfl_xor(ss, 32);
;                 if (fq == 0) ssqs[(size_t)row * 32 + un.pn * 4 + wc] = ss;
.LBB0_1068:
	s_or_b64 exec, exec, s[30:31]
	v_or_b32_e32 v50, 48, v86
	s_waitcnt lgkmcnt(0)
	v_ashrrev_i32_e32 v51, 31, v50
	v_lshlrev_b64 v[52:53], 11, v[50:51]
	v_lshl_add_u64 v[52:53], s[0:1], 0, v[52:53]
	v_lshl_add_u64 v[52:53], v[52:53], 0, v[84:85]
	v_add_f32_e32 v42, v42, v26
	v_add_f32_e32 v43, v43, v27
	v_add_f32_e32 v46, v46, v30
	v_add_f32_e32 v47, v47, v31
	v_add_f32_e32 v44, v44, v28
	v_add_f32_e32 v49, v49, v33
	v_add_f32_e32 v45, v45, v29
	v_mul_f32_e32 v42, 0xbfb8aa3b, v42
	v_mul_f32_e32 v43, 0xbfb8aa3b, v43
	v_add_f32_e32 v48, v48, v32
	v_mul_f32_e32 v46, 0xbfb8aa3b, v46
	v_mul_f32_e32 v47, 0xbfb8aa3b, v47
	v_mul_f32_e32 v44, 0xbfb8aa3b, v44
	v_mul_f32_e32 v49, 0xbfb8aa3b, v49
	v_mul_f32_e32 v45, 0xbfb8aa3b, v45
	v_exp_f32_e32 v42, v42
	v_exp_f32_e32 v43, v43
	v_mul_f32_e32 v48, 0xbfb8aa3b, v48
	v_exp_f32_e32 v46, v46
	v_exp_f32_e32 v47, v47
	v_exp_f32_e32 v44, v44
	v_exp_f32_e32 v49, v49
	v_exp_f32_e32 v45, v45
	v_exp_f32_e32 v48, v48
	v_add_f32_e32 v42, 1.0, v42
	v_add_f32_e32 v43, 1.0, v43
	v_add_f32_e32 v46, 1.0, v46
	v_add_f32_e32 v47, 1.0, v47
	v_add_f32_e32 v44, 1.0, v44
	v_add_f32_e32 v49, 1.0, v49
	v_add_f32_e32 v45, 1.0, v45
	v_rcp_f32_e32 v42, v42
	v_rcp_f32_e32 v43, v43
	v_add_f32_e32 v48, 1.0, v48
	v_rcp_f32_e32 v46, v46
	v_rcp_f32_e32 v47, v47
	v_rcp_f32_e32 v44, v44
	v_rcp_f32_e32 v49, v49
	v_rcp_f32_e32 v45, v45
	v_rcp_f32_e32 v48, v48
	v_lshlrev_b32_e32 v58, 16, v110
	v_and_b32_e32 v54, 0xffff0000, v110
	v_lshlrev_b32_e32 v56, 16, v108
	v_and_b32_e32 v52, 0xffff0000, v108
	v_lshlrev_b32_e32 v57, 16, v109
	v_and_b32_e32 v53, 0xffff0000, v109
	v_lshlrev_b32_e32 v59, 16, v111
	v_and_b32_e32 v55, 0xffff0000, v111
	v_mul_f32_e32 v42, v42, v58
	v_mul_f32_e32 v43, v43, v54
	v_mul_f32_e32 v46, v46, v56
	v_mul_f32_e32 v47, v47, v52
	v_mul_f32_e32 v52, v44, v59
	v_mul_f32_e32 v49, v49, v53
	v_mul_f32_e32 v53, v45, v55
	v_mul_f32_e32 v44, v42, v42
	v_mul_f32_e32 v45, v43, v43
	v_mul_f32_e32 v48, v48, v57
	v_mul_f32_e32 v54, v52, v52
	v_fmac_f32_e32 v44, v46, v46
	v_fmac_f32_e32 v45, v47, v47
	v_mul_f32_e32 v55, v53, v53
	v_fmac_f32_e32 v54, v48, v48
	v_add_f32_e32 v44, v44, v45
	v_add_f32_e32 v44, v54, v44
	v_fmac_f32_e32 v55, v49, v49
	v_add_f32_e32 v54, v55, v44
	ds_bpermute_b32 v55, v68, v54
	v_cvt_pk_bf16_f32 v44, v46, v47
	v_cvt_pk_bf16_f32 v45, v48, v49
	v_cvt_pk_bf16_f32 v46, v42, v43
	v_lshlrev_b64 v[48:49], 12, v[50:51]
	s_waitcnt lgkmcnt(0)
	v_add_f32_e32 v42, v54, v55
	ds_bpermute_b32 v43, v69, v42
	v_lshl_add_u64 v[48:49], s[22:23], 0, v[48:49]
	v_lshl_add_u64 v[48:49], v[48:49], 0, v[84:85]
	v_cvt_pk_bf16_f32 v47, v52, v53
	global_store_dwordx4 v[48:49], v[44:47], off offset:2048 sc0 sc1
	s_and_saveexec_b64 s[30:31], s[36:37]
	s_cbranch_execz .LBB0_1070
	v_lshlrev_b64 v[44:45], 7, v[50:51]
	v_lshl_add_u64 v[44:45], s[24:25], 0, v[44:45]
	v_lshl_add_u64 v[44:45], s[48:49], 2, v[44:45]
	s_lshl_b32 s74, s64, 2
	v_lshl_add_u64 v[44:45], v[44:45], 0, s[74:75]
	s_waitcnt lgkmcnt(0)
	v_add_f32_e32 v42, v42, v43
	global_store_dword v[44:45], v42, off
.LBB0_1070:
	s_or_b64 exec, exec, s[30:31]
	v_add_u32_e32 v42, 0x80, v86
	s_waitcnt lgkmcnt(0)
	v_ashrrev_i32_e32 v43, 31, v42
	v_lshlrev_b64 v[44:45], 11, v[42:43]
	v_lshl_add_u64 v[44:45], s[0:1], 0, v[44:45]
	v_lshl_add_u64 v[44:45], v[44:45], 0, v[84:85]
	v_add_f32_e32 v34, v34, v26
	v_add_f32_e32 v35, v35, v27
	v_add_f32_e32 v38, v38, v30
	v_add_f32_e32 v39, v39, v31
	v_add_f32_e32 v36, v36, v28
	v_add_f32_e32 v41, v41, v33
	v_add_f32_e32 v37, v37, v29
	v_mul_f32_e32 v34, 0xbfb8aa3b, v34
	v_mul_f32_e32 v35, 0xbfb8aa3b, v35
	v_add_f32_e32 v40, v40, v32
	v_mul_f32_e32 v38, 0xbfb8aa3b, v38
	v_mul_f32_e32 v39, 0xbfb8aa3b, v39
	v_mul_f32_e32 v36, 0xbfb8aa3b, v36
	v_mul_f32_e32 v41, 0xbfb8aa3b, v41
	v_mul_f32_e32 v37, 0xbfb8aa3b, v37
	v_exp_f32_e32 v34, v34
	v_exp_f32_e32 v35, v35
	v_mul_f32_e32 v40, 0xbfb8aa3b, v40
	v_exp_f32_e32 v38, v38
	v_exp_f32_e32 v39, v39
	v_exp_f32_e32 v36, v36
	v_exp_f32_e32 v41, v41
	v_exp_f32_e32 v37, v37
	v_exp_f32_e32 v40, v40
	v_add_f32_e32 v34, 1.0, v34
	v_add_f32_e32 v35, 1.0, v35
	v_add_f32_e32 v38, 1.0, v38
	v_add_f32_e32 v39, 1.0, v39
	v_add_f32_e32 v36, 1.0, v36
	v_add_f32_e32 v41, 1.0, v41
	v_add_f32_e32 v37, 1.0, v37
	v_rcp_f32_e32 v34, v34
	v_rcp_f32_e32 v35, v35
	v_add_f32_e32 v40, 1.0, v40
	v_rcp_f32_e32 v38, v38
	v_rcp_f32_e32 v39, v39
	v_rcp_f32_e32 v36, v36
	v_rcp_f32_e32 v41, v41
	v_rcp_f32_e32 v37, v37
	v_rcp_f32_e32 v40, v40
	v_lshlrev_b32_e32 v50, 16, v114
	v_and_b32_e32 v46, 0xffff0000, v114
	v_lshlrev_b32_e32 v48, 16, v112
	v_and_b32_e32 v44, 0xffff0000, v112
	v_lshlrev_b32_e32 v49, 16, v113
	v_and_b32_e32 v45, 0xffff0000, v113
	v_lshlrev_b32_e32 v51, 16, v115
	v_and_b32_e32 v47, 0xffff0000, v115
	v_mul_f32_e32 v34, v34, v50
	v_mul_f32_e32 v35, v35, v46
	v_mul_f32_e32 v38, v38, v48
	v_mul_f32_e32 v39, v39, v44
	v_mul_f32_e32 v44, v36, v51
	v_mul_f32_e32 v41, v41, v45
	v_mul_f32_e32 v45, v37, v47
	v_mul_f32_e32 v36, v34, v34
	v_mul_f32_e32 v37, v35, v35
	v_mul_f32_e32 v40, v40, v49
	v_mul_f32_e32 v46, v44, v44
	v_fmac_f32_e32 v36, v38, v38
	v_fmac_f32_e32 v37, v39, v39
	v_mul_f32_e32 v47, v45, v45
	v_fmac_f32_e32 v46, v40, v40
	v_add_f32_e32 v36, v36, v37
	v_add_f32_e32 v36, v46, v36
	v_fmac_f32_e32 v47, v41, v41
	v_add_f32_e32 v46, v47, v36
	ds_bpermute_b32 v47, v68, v46
	v_cvt_pk_bf16_f32 v36, v38, v39
	v_cvt_pk_bf16_f32 v37, v40, v41
	v_cvt_pk_bf16_f32 v38, v34, v35
	v_lshlrev_b64 v[40:41], 12, v[42:43]
	s_waitcnt lgkmcnt(0)
	v_add_f32_e32 v34, v46, v47
	ds_bpermute_b32 v35, v69, v34
	v_lshl_add_u64 v[40:41], s[22:23], 0, v[40:41]
	v_lshl_add_u64 v[40:41], v[40:41], 0, v[84:85]
	v_cvt_pk_bf16_f32 v39, v44, v45
	global_store_dwordx4 v[40:41], v[36:39], off offset:2048 sc0 sc1
	s_and_saveexec_b64 s[30:31], s[36:37]
	s_cbranch_execz .LBB0_1072
	v_lshlrev_b64 v[36:37], 7, v[42:43]
	v_lshl_add_u64 v[36:37], s[24:25], 0, v[36:37]
	v_lshl_add_u64 v[36:37], s[48:49], 2, v[36:37]
	s_lshl_b32 s74, s64, 2
	v_lshl_add_u64 v[36:37], v[36:37], 0, s[74:75]
	s_waitcnt lgkmcnt(0)
	v_add_f32_e32 v34, v34, v35
	global_store_dword v[36:37], v34, off
; __device__ __forceinline__ u32x4 pack8(f32x4 a, f32x4 b) { u32x4 w; w.x = pk2(a[0], a[1]); w.y = pk2(a[2], a[3]); w.z = pk2(b[0], b[1]); w.w = pk2(b[2], b[3]); return w; }
;     __device__ __forceinline__ void operator()(const f32x4 (&acc)[2][2][4][2], const Unit& un, int wr, int wc, int fr, int fq, int lane) const {
;     ...
;         for (int ai = 0; ai < 2; ++ai)
; #pragma unroll
;             for (int m = 0; m < 4; ++m) {
;                 const int row = un.pm * 256 + ai * 128 + wr * 64 + m * 16 + fr; float ss = 0.f;
;                 const size_t off = (size_t)row * 1024 + c0, offs = (size_t)row * 2048 + 1024 + c0;
;                 const u32x4 gw = *(const u32x4*)(gb + off);
;                 const f32x4 g0 = (f32x4){bflo(gw.x), bfhi(gw.x), bflo(gw.y), bfhi(gw.y)}, g1 = (f32x4){bflo(gw.z), bfhi(gw.z), bflo(gw.w), bfhi(gw.w)};
;                 const f32x4 z0 = acc[ai][0][m][0] + bv0, z1 = acc[ai][0][m][1] + bv1;
;                 f32x4 o0, o1;
; #pragma unroll
;                 for (int j = 0; j < 4; ++j) { o0[j] = g0[j] * __builtin_amdgcn_rcpf(1.f + __expf(-z0[j])); o1[j] = g1[j] * __builtin_amdgcn_rcpf(1.f + __expf(-z1[j])); ss += o0[j] * o0[j] + o1[j] * o1[j]; }
;                 *(u32x4*)(s + offs) = pack8(o0, o1);
;                 ss += __shfl_xor(ss, 16); ss += __shfl_xor(ss, 32);
;                 if (fq == 0) ssqs[(size_t)row * 32 + un.pn * 4 + wc] = ss;
.LBB0_1072:
	s_or_b64 exec, exec, s[30:31]
	v_add_u32_e32 v34, 0x90, v86
	s_waitcnt lgkmcnt(0)
	v_ashrrev_i32_e32 v35, 31, v34
	v_lshlrev_b64 v[36:37], 11, v[34:35]
	v_lshl_add_u64 v[36:37], s[0:1], 0, v[36:37]
	v_lshl_add_u64 v[36:37], v[36:37], 0, v[84:85]
	v_add_f32_e32 v16, v16, v26
	v_add_f32_e32 v17, v17, v27
	v_add_f32_e32 v20, v20, v30
	v_add_f32_e32 v21, v21, v31
	v_add_f32_e32 v18, v18, v28
	v_add_f32_e32 v23, v23, v33
	v_add_f32_e32 v19, v19, v29
	v_mul_f32_e32 v16, 0xbfb8aa3b, v16
	v_mul_f32_e32 v17, 0xbfb8aa3b, v17
	v_add_f32_e32 v22, v22, v32
	v_mul_f32_e32 v20, 0xbfb8aa3b, v20
	v_mul_f32_e32 v21, 0xbfb8aa3b, v21
	v_mul_f32_e32 v18, 0xbfb8aa3b, v18
	v_mul_f32_e32 v23, 0xbfb8aa3b, v23
	v_mul_f32_e32 v19, 0xbfb8aa3b, v19
	v_exp_f32_e32 v16, v16
	v_exp_f32_e32 v17, v17
	v_mul_f32_e32 v22, 0xbfb8aa3b, v22
	v_exp_f32_e32 v20, v20
	v_exp_f32_e32 v21, v21
	v_exp_f32_e32 v18, v18
	v_exp_f32_e32 v23, v23
	v_exp_f32_e32 v19, v19
	v_exp_f32_e32 v22, v22
	v_add_f32_e32 v16, 1.0, v16
	v_add_f32_e32 v17, 1.0, v17
	v_add_f32_e32 v20, 1.0, v20
	v_add_f32_e32 v21, 1.0, v21
	v_add_f32_e32 v18, 1.0, v18
	v_add_f32_e32 v23, 1.0, v23
	v_add_f32_e32 v19, 1.0, v19
	v_rcp_f32_e32 v16, v16
	v_rcp_f32_e32 v17, v17
	v_add_f32_e32 v22, 1.0, v22
	v_rcp_f32_e32 v20, v20
	v_rcp_f32_e32 v21, v21
	v_rcp_f32_e32 v18, v18
	v_rcp_f32_e32 v23, v23
	v_rcp_f32_e32 v19, v19
	v_rcp_f32_e32 v22, v22
	v_lshlrev_b32_e32 v42, 16, v118
	v_and_b32_e32 v38, 0xffff0000, v118
	v_lshlrev_b32_e32 v40, 16, v116
	v_and_b32_e32 v36, 0xffff0000, v116
	v_lshlrev_b32_e32 v41, 16, v117
	v_and_b32_e32 v37, 0xffff0000, v117
	v_lshlrev_b32_e32 v43, 16, v119
	v_and_b32_e32 v39, 0xffff0000, v119
	v_mul_f32_e32 v16, v16, v42
	v_mul_f32_e32 v17, v17, v38
	v_mul_f32_e32 v20, v20, v40
	v_mul_f32_e32 v21, v21, v36
	v_mul_f32_e32 v36, v18, v43
	v_mul_f32_e32 v23, v23, v37
	v_mul_f32_e32 v37, v19, v39
	v_mul_f32_e32 v18, v16, v16
	v_mul_f32_e32 v19, v17, v17
	v_mul_f32_e32 v22, v22, v41
	v_mul_f32_e32 v38, v36, v36
	v_fmac_f32_e32 v18, v20, v20
	v_fmac_f32_e32 v19, v21, v21
	v_mul_f32_e32 v39, v37, v37
	v_fmac_f32_e32 v38, v22, v22
	v_add_f32_e32 v18, v18, v19
	v_add_f32_e32 v18, v38, v18
	v_fmac_f32_e32 v39, v23, v23
	v_add_f32_e32 v38, v39, v18
	ds_bpermute_b32 v39, v68, v38
	v_cvt_pk_bf16_f32 v18, v20, v21
	v_cvt_pk_bf16_f32 v19, v22, v23
	v_cvt_pk_bf16_f32 v20, v16, v17
	v_lshlrev_b64 v[22:23], 12, v[34:35]
	s_waitcnt lgkmcnt(0)
	v_add_f32_e32 v16, v38, v39
	ds_bpermute_b32 v17, v69, v16
	v_lshl_add_u64 v[22:23], s[22:23], 0, v[22:23]
	v_lshl_add_u64 v[22:23], v[22:23], 0, v[84:85]
	v_cvt_pk_bf16_f32 v21, v36, v37
	global_store_dwordx4 v[22:23], v[18:21], off offset:2048 sc0 sc1
	s_and_saveexec_b64 s[30:31], s[36:37]
	s_cbranch_execz .LBB0_1074
	v_lshlrev_b64 v[18:19], 7, v[34:35]
	v_lshl_add_u64 v[18:19], s[24:25], 0, v[18:19]
	v_lshl_add_u64 v[18:19], s[48:49], 2, v[18:19]
	s_lshl_b32 s74, s64, 2
	v_lshl_add_u64 v[18:19], v[18:19], 0, s[74:75]
	s_waitcnt lgkmcnt(0)
	v_add_f32_e32 v16, v16, v17
	global_store_dword v[18:19], v16, off
; __device__ __forceinline__ u32x4 pack8(f32x4 a, f32x4 b) { u32x4 w; w.x = pk2(a[0], a[1]); w.y = pk2(a[2], a[3]); w.z = pk2(b[0], b[1]); w.w = pk2(b[2], b[3]); return w; }
;     __device__ __forceinline__ void operator()(const f32x4 (&acc)[2][2][4][2], const Unit& un, int wr, int wc, int fr, int fq, int lane) const {
;     ...
;         for (int ai = 0; ai < 2; ++ai)
; #pragma unroll
;             for (int m = 0; m < 4; ++m) {
;                 const int row = un.pm * 256 + ai * 128 + wr * 64 + m * 16 + fr; float ss = 0.f;
;                 const size_t off = (size_t)row * 1024 + c0, offs = (size_t)row * 2048 + 1024 + c0;
;                 const u32x4 gw = *(const u32x4*)(gb + off);
;                 const f32x4 g0 = (f32x4){bflo(gw.x), bfhi(gw.x), bflo(gw.y), bfhi(gw.y)}, g1 = (f32x4){bflo(gw.z), bfhi(gw.z), bflo(gw.w), bfhi(gw.w)};
;                 const f32x4 z0 = acc[ai][0][m][0] + bv0, z1 = acc[ai][0][m][1] + bv1;
;                 f32x4 o0, o1;
; #pragma unroll
;                 for (int j = 0; j < 4; ++j) { o0[j] = g0[j] * __builtin_amdgcn_rcpf(1.f + __expf(-z0[j])); o1[j] = g1[j] * __builtin_amdgcn_rcpf(1.f + __expf(-z1[j])); ss += o0[j] * o0[j] + o1[j] * o1[j]; }
;                 *(u32x4*)(s + offs) = pack8(o0, o1);
;                 ss += __shfl_xor(ss, 16); ss += __shfl_xor(ss, 32);
;                 if (fq == 0) ssqs[(size_t)row * 32 + un.pn * 4 + wc] = ss;
.LBB0_1074:
	s_or_b64 exec, exec, s[30:31]
	v_add_u32_e32 v16, 0xa0, v86
	s_waitcnt lgkmcnt(0)
	v_ashrrev_i32_e32 v17, 31, v16
	v_lshlrev_b64 v[18:19], 11, v[16:17]
	v_lshl_add_u64 v[18:19], s[0:1], 0, v[18:19]
	v_lshl_add_u64 v[18:19], v[18:19], 0, v[84:85]
	v_add_f32_e32 v8, v8, v26
	v_add_f32_e32 v9, v9, v27
	v_add_f32_e32 v12, v12, v30
	v_add_f32_e32 v13, v13, v31
	v_add_f32_e32 v10, v10, v28
	v_add_f32_e32 v15, v15, v33
	v_add_f32_e32 v11, v11, v29
	v_mul_f32_e32 v8, 0xbfb8aa3b, v8
	v_mul_f32_e32 v9, 0xbfb8aa3b, v9
	v_add_f32_e32 v14, v14, v32
	v_mul_f32_e32 v12, 0xbfb8aa3b, v12
	v_mul_f32_e32 v13, 0xbfb8aa3b, v13
	v_mul_f32_e32 v10, 0xbfb8aa3b, v10
	v_mul_f32_e32 v15, 0xbfb8aa3b, v15
	v_mul_f32_e32 v11, 0xbfb8aa3b, v11
	v_exp_f32_e32 v8, v8
	v_exp_f32_e32 v9, v9
	v_mul_f32_e32 v14, 0xbfb8aa3b, v14
	v_exp_f32_e32 v12, v12
	v_exp_f32_e32 v13, v13
	v_exp_f32_e32 v10, v10
	v_exp_f32_e32 v15, v15
	v_exp_f32_e32 v11, v11
	v_exp_f32_e32 v14, v14
	v_add_f32_e32 v8, 1.0, v8
	v_add_f32_e32 v9, 1.0, v9
	v_add_f32_e32 v12, 1.0, v12
	v_add_f32_e32 v13, 1.0, v13
	v_add_f32_e32 v10, 1.0, v10
	v_add_f32_e32 v15, 1.0, v15
	v_add_f32_e32 v11, 1.0, v11
	v_rcp_f32_e32 v8, v8
	v_rcp_f32_e32 v9, v9
	v_add_f32_e32 v14, 1.0, v14
	v_rcp_f32_e32 v12, v12
	v_rcp_f32_e32 v13, v13
	v_rcp_f32_e32 v10, v10
	v_rcp_f32_e32 v15, v15
	v_rcp_f32_e32 v11, v11
	v_rcp_f32_e32 v14, v14
	v_lshlrev_b32_e32 v34, 16, v122
	v_and_b32_e32 v20, 0xffff0000, v122
	v_lshlrev_b32_e32 v22, 16, v120
	v_and_b32_e32 v18, 0xffff0000, v120
	v_lshlrev_b32_e32 v23, 16, v121
	v_and_b32_e32 v19, 0xffff0000, v121
	v_lshlrev_b32_e32 v35, 16, v123
	v_and_b32_e32 v21, 0xffff0000, v123
	v_mul_f32_e32 v8, v8, v34
	v_mul_f32_e32 v9, v9, v20
	v_mul_f32_e32 v12, v12, v22
	v_mul_f32_e32 v13, v13, v18
	v_mul_f32_e32 v18, v10, v35
	v_mul_f32_e32 v15, v15, v19
	v_mul_f32_e32 v19, v11, v21
	v_mul_f32_e32 v10, v8, v8
	v_mul_f32_e32 v11, v9, v9
	v_mul_f32_e32 v14, v14, v23
	v_mul_f32_e32 v20, v18, v18
	v_fmac_f32_e32 v10, v12, v12
	v_fmac_f32_e32 v11, v13, v13
	v_mul_f32_e32 v21, v19, v19
	v_fmac_f32_e32 v20, v14, v14
	v_add_f32_e32 v10, v10, v11
	v_add_f32_e32 v10, v20, v10
	v_fmac_f32_e32 v21, v15, v15
	v_add_f32_e32 v20, v21, v10
	ds_bpermute_b32 v21, v68, v20
	v_cvt_pk_bf16_f32 v10, v12, v13
	v_cvt_pk_bf16_f32 v11, v14, v15
	v_cvt_pk_bf16_f32 v12, v8, v9
	v_lshlrev_b64 v[14:15], 12, v[16:17]
	s_waitcnt lgkmcnt(0)
	v_add_f32_e32 v8, v20, v21
	ds_bpermute_b32 v9, v69, v8
	v_lshl_add_u64 v[14:15], s[22:23], 0, v[14:15]
	v_lshl_add_u64 v[14:15], v[14:15], 0, v[84:85]
	v_cvt_pk_bf16_f32 v13, v18, v19
	global_store_dwordx4 v[14:15], v[10:13], off offset:2048 sc0 sc1
	s_and_saveexec_b64 s[30:31], s[36:37]
	s_cbranch_execz .LBB0_1076
	v_lshlrev_b64 v[10:11], 7, v[16:17]
	v_lshl_add_u64 v[10:11], s[24:25], 0, v[10:11]
	v_lshl_add_u64 v[10:11], s[48:49], 2, v[10:11]
	s_lshl_b32 s74, s64, 2
	v_lshl_add_u64 v[10:11], v[10:11], 0, s[74:75]
	s_waitcnt lgkmcnt(0)
	v_add_f32_e32 v8, v8, v9
	global_store_dword v[10:11], v8, off
.LBB0_1076:
	s_or_b64 exec, exec, s[30:31]
	v_add_u32_e32 v8, 0xb0, v86
	s_waitcnt lgkmcnt(0)
	v_ashrrev_i32_e32 v9, 31, v8
	v_lshlrev_b64 v[10:11], 11, v[8:9]
	v_lshl_add_u64 v[10:11], s[0:1], 0, v[10:11]
	v_lshl_add_u64 v[10:11], v[10:11], 0, v[84:85]
	v_add_f32_e32 v0, v0, v26
	v_add_f32_e32 v1, v1, v27
	v_add_f32_e32 v4, v4, v30
	v_add_f32_e32 v5, v5, v31
	v_add_f32_e32 v2, v2, v28
	v_add_f32_e32 v7, v7, v33
	v_add_f32_e32 v3, v3, v29
	v_mul_f32_e32 v0, 0xbfb8aa3b, v0
	v_mul_f32_e32 v1, 0xbfb8aa3b, v1
	v_add_f32_e32 v6, v6, v32
	v_mul_f32_e32 v4, 0xbfb8aa3b, v4
	v_mul_f32_e32 v5, 0xbfb8aa3b, v5
	v_mul_f32_e32 v2, 0xbfb8aa3b, v2
	v_mul_f32_e32 v7, 0xbfb8aa3b, v7
	v_mul_f32_e32 v3, 0xbfb8aa3b, v3
	v_exp_f32_e32 v0, v0
	v_exp_f32_e32 v1, v1
	v_mul_f32_e32 v6, 0xbfb8aa3b, v6
	v_exp_f32_e32 v4, v4
	v_exp_f32_e32 v5, v5
	v_exp_f32_e32 v2, v2
	v_exp_f32_e32 v7, v7
	v_exp_f32_e32 v3, v3
	v_exp_f32_e32 v6, v6
	v_add_f32_e32 v0, 1.0, v0
	v_add_f32_e32 v1, 1.0, v1
	v_add_f32_e32 v4, 1.0, v4
	v_add_f32_e32 v5, 1.0, v5
	v_add_f32_e32 v2, 1.0, v2
	v_add_f32_e32 v7, 1.0, v7
	v_add_f32_e32 v3, 1.0, v3
	v_rcp_f32_e32 v0, v0
	v_rcp_f32_e32 v1, v1
	v_add_f32_e32 v6, 1.0, v6
	v_rcp_f32_e32 v4, v4
	v_rcp_f32_e32 v5, v5
	v_rcp_f32_e32 v2, v2
	v_rcp_f32_e32 v7, v7
	v_rcp_f32_e32 v3, v3
	v_rcp_f32_e32 v6, v6
	v_lshlrev_b32_e32 v16, 16, v126
	v_and_b32_e32 v12, 0xffff0000, v126
	v_lshlrev_b32_e32 v14, 16, v124
	v_and_b32_e32 v10, 0xffff0000, v124
	v_lshlrev_b32_e32 v15, 16, v125
	v_and_b32_e32 v11, 0xffff0000, v125
	v_lshlrev_b32_e32 v17, 16, v127
	v_and_b32_e32 v13, 0xffff0000, v127
	v_mul_f32_e32 v0, v0, v16
	v_mul_f32_e32 v1, v1, v12
	v_mul_f32_e32 v4, v4, v14
	v_mul_f32_e32 v5, v5, v10
	v_mul_f32_e32 v10, v2, v17
	v_mul_f32_e32 v7, v7, v11
	v_mul_f32_e32 v11, v3, v13
	v_mul_f32_e32 v2, v0, v0
	v_mul_f32_e32 v3, v1, v1
	v_mul_f32_e32 v6, v6, v15
	v_mul_f32_e32 v12, v10, v10
	v_fmac_f32_e32 v2, v4, v4
	v_fmac_f32_e32 v3, v5, v5
	v_mul_f32_e32 v13, v11, v11
	v_fmac_f32_e32 v12, v6, v6
	v_add_f32_e32 v2, v2, v3
	v_add_f32_e32 v2, v12, v2
	v_fmac_f32_e32 v13, v7, v7
	v_add_f32_e32 v12, v13, v2
	ds_bpermute_b32 v13, v68, v12
	v_cvt_pk_bf16_f32 v2, v4, v5
	v_cvt_pk_bf16_f32 v3, v6, v7
	v_cvt_pk_bf16_f32 v4, v0, v1
	v_lshlrev_b64 v[6:7], 12, v[8:9]
	s_waitcnt lgkmcnt(0)
	v_add_f32_e32 v0, v12, v13
	ds_bpermute_b32 v1, v69, v0
	v_lshl_add_u64 v[6:7], s[22:23], 0, v[6:7]
	v_lshl_add_u64 v[6:7], v[6:7], 0, v[84:85]
	v_cvt_pk_bf16_f32 v5, v10, v11
	global_store_dwordx4 v[6:7], v[2:5], off offset:2048 sc0 sc1
	s_and_saveexec_b64 s[30:31], s[36:37]
	s_cbranch_execz .LBB0_1078
	v_lshlrev_b64 v[2:3], 7, v[8:9]
	v_lshl_add_u64 v[2:3], s[24:25], 0, v[2:3]
	v_lshl_add_u64 v[2:3], s[48:49], 2, v[2:3]
	s_lshl_b32 s74, s64, 2
	v_lshl_add_u64 v[2:3], v[2:3], 0, s[74:75]
	s_waitcnt lgkmcnt(0)
	v_add_f32_e32 v0, v0, v1
	global_store_dword v[2:3], v0, off

; __device__ __forceinline__ u32x4 pack8(f32x4 a, f32x4 b) { u32x4 w; w.x = pk2(a[0], a[1]); w.y = pk2(a[2], a[3]); w.z = pk2(b[0], b[1]); w.w = pk2(b[2], b[3]); return w; }
;     __device__ __forceinline__ void operator()(const f32x4 (&acc)[2][2][4][2], const Unit& un, int wr, int wc, int fr, int fq, int lane) const {
;         const int c0 = un.pn * 256 + wc * 32 + 8 * fq;
; #pragma unroll
;         for (int ai = 0; ai < 2; ++ai)
; #pragma unroll
;             for (int m = 0; m < 4; ++m) {
;                 const int row = un.pm * 256 + ai * 128 + wr * 64 + m * 16 + fr; float ss = 0.f;
; #pragma unroll
;                 for (int bj = 0; bj < 2; ++bj) {
;                     const size_t off = (size_t)row * DM + c0 + bj * 128; const u32x4 xw = *(const u32x4*)(xb + off);
;                     const f32x4 o0 = (f32x4){bflo(xw.x), bfhi(xw.x), bflo(xw.y), bfhi(xw.y)} + acc[ai][bj][m][0], o1 = (f32x4){bflo(xw.z), bfhi(xw.z), bflo(xw.w), bfhi(xw.w)} + acc[ai][bj][m][1];
;                     if (out) { *(f32x4*)(out + off) = o0; *(f32x4*)(out + off + 4) = o1; }
;                     else { *(u32x4*)(xb + off) = pack8(o0, o1);
;                         ss += ((o0[0] * o0[0] + o0[1] * o0[1]) + (o0[2] * o0[2] + o0[3] * o0[3])) + ((o1[0] * o1[0] + o1[1] * o1[1]) + (o1[2] * o1[2] + o1[3] * o1[3])); }
;                 }
;                 if (!out) { ss += __shfl_xor(ss, 16); ss += __shfl_xor(ss, 32); if (fq == 0) ssqx[(size_t)row * 32 + un.pn * 4 + wc] = ss; }
.LBB0_1360:
	v_lshl_add_u32 v142, s90, 8, v150
	v_lshl_or_b32 v140, s88, 8, v152
	v_ashrrev_i32_e32 v143, 31, v142
	v_ashrrev_i32_e32 v141, 31, v140
	v_lshlrev_b64 v[144:145], 11, v[142:143]
	v_lshl_add_u64 v[146:147], v[144:145], 0, v[140:141]
	v_lshl_add_u64 v[148:149], v[146:147], 1, s[0:1]
	global_load_dwordx4 v[154:157], v[148:149], off
	global_load_dwordx4 v[158:161], v[148:149], off offset:256
	s_mov_b64 s[30:31], 0x10000
	v_lshl_add_u64 v[144:145], v[148:149], 0, s[30:31]
	global_load_dwordx4 v[162:165], v[144:145], off
	global_load_dwordx4 v[166:169], v[144:145], off offset:256
	v_lshl_add_u64 v[144:145], v[144:145], 0, s[30:31]
	global_load_dwordx4 v[170:173], v[144:145], off
	global_load_dwordx4 v[174:177], v[144:145], off offset:256
	v_lshl_add_u64 v[144:145], v[144:145], 0, s[30:31]
	global_load_dwordx4 v[178:181], v[144:145], off
	global_load_dwordx4 v[182:185], v[144:145], off offset:256
	s_mov_b64 s[30:31], 0x50000
	v_lshl_add_u64 v[144:145], v[144:145], 0, s[30:31]
	s_mov_b64 s[30:31], 0x10000
	global_load_dwordx4 v[186:189], v[144:145], off
	global_load_dwordx4 v[190:193], v[144:145], off offset:256
	v_lshl_add_u64 v[144:145], v[144:145], 0, s[30:31]
	global_load_dwordx4 v[194:197], v[144:145], off
	global_load_dwordx4 v[206:209], v[144:145], off offset:256
	v_lshl_add_u64 v[144:145], v[144:145], 0, s[30:31]
	global_load_dwordx4 v[210:213], v[144:145], off
	global_load_dwordx4 v[214:217], v[144:145], off offset:256
	v_lshl_add_u64 v[144:145], v[144:145], 0, s[30:31]
	global_load_dwordx4 v[226:229], v[144:145], off
	global_load_dwordx4 v[230:233], v[144:145], off offset:256
	s_mov_b64 s[30:31], -1
	s_andn2_b64 vcc, exec, s[48:49]
	s_waitcnt vmcnt(0)
	v_lshlrev_b32_e32 v144, 16, v154
	v_and_b32_e32 v145, 0xffff0000, v154
	v_lshlrev_b32_e32 v154, 16, v155
	v_and_b32_e32 v155, 0xffff0000, v155
	v_pk_add_f32 v[126:127], v[126:127], v[144:145]
	v_lshlrev_b32_e32 v144, 16, v156
	v_and_b32_e32 v145, 0xffff0000, v156
	v_pk_add_f32 v[128:129], v[128:129], v[154:155]
	v_lshlrev_b32_e32 v154, 16, v157
	v_and_b32_e32 v155, 0xffff0000, v157
	v_pk_add_f32 v[122:123], v[122:123], v[144:145]
	v_cndmask_b32_e64 v144, 0, 1, s[48:49]
	v_pk_add_f32 v[124:125], v[124:125], v[154:155]
	v_cmp_ne_u32_e64 s[42:43], 1, v144
	v_lshl_add_u64 v[144:145], v[146:147], 2, s[24:25]
	s_cbranch_vccnz .LBB0_1362
	s_mov_b64 s[30:31], 0
	global_store_dwordx4 v[144:145], v[126:129], off sc0 sc1
	global_store_dwordx4 v[144:145], v[122:125], off offset:16 sc0 sc1
.LBB0_1362:
	s_andn2_b64 vcc, exec, s[30:31]
	v_mov_b32_e32 v154, 0
	s_cbranch_vccnz .LBB0_1364
	v_cvt_pk_bf16_f32 v154, v126, v127
	v_cvt_pk_bf16_f32 v155, v128, v129
	v_cvt_pk_bf16_f32 v156, v122, v123
	v_cvt_pk_bf16_f32 v157, v124, v125
	global_store_dwordx4 v[148:149], v[154:157], off sc0 sc1
	v_mov_b32_e32 v149, v122
	v_mov_b32_e32 v122, v127
	v_mov_b32_e32 v127, v124
	v_mov_b32_e32 v124, v129
	v_mov_b32_e32 v148, v126
	v_pk_mul_f32 v[122:123], v[122:123], v[122:123]
	v_mov_b32_e32 v126, v128
	v_pk_mul_f32 v[124:125], v[124:125], v[124:125]
	v_pk_fma_f32 v[122:123], v[148:149], v[148:149], v[122:123]
	v_pk_fma_f32 v[124:125], v[126:127], v[126:127], v[124:125]
	s_nop 0
	v_pk_add_f32 v[122:123], v[122:123], v[124:125]
	s_nop 0
	v_add_f32_e32 v154, v122, v123
.LBB0_1364:
	v_lshlrev_b64 v[122:123], 1, v[146:147]
	v_or_b32_e32 v122, 0x100, v122
	v_lshl_add_u64 v[122:123], s[0:1], 0, v[122:123]
	s_mov_b64 s[30:31], -1
	s_and_b64 vcc, exec, s[42:43]
	v_lshlrev_b32_e32 v128, 16, v158
	v_and_b32_e32 v129, 0xffff0000, v158
	v_lshlrev_b32_e32 v124, 16, v159
	v_and_b32_e32 v125, 0xffff0000, v159
	v_pk_add_f32 v[120:121], v[120:121], v[124:125]
	v_lshlrev_b32_e32 v124, 16, v160
	v_and_b32_e32 v125, 0xffff0000, v160
	v_lshlrev_b32_e32 v126, 16, v161
	v_and_b32_e32 v127, 0xffff0000, v161
	v_pk_add_f32 v[118:119], v[118:119], v[128:129]
	v_pk_add_f32 v[116:117], v[116:117], v[126:127]
	v_pk_add_f32 v[114:115], v[114:115], v[124:125]
	s_cbranch_vccnz .LBB0_1366
	s_mov_b64 s[30:31], 0
	global_store_dwordx4 v[144:145], v[118:121], off offset:512 sc0 sc1
	global_store_dwordx4 v[144:145], v[114:117], off offset:528 sc0 sc1
.LBB0_1366:
	s_andn2_b64 vcc, exec, s[30:31]
	s_cbranch_vccnz .LBB0_1368
	v_cvt_pk_bf16_f32 v124, v118, v119
	v_cvt_pk_bf16_f32 v125, v120, v121
	v_cvt_pk_bf16_f32 v126, v114, v115
	v_cvt_pk_bf16_f32 v127, v116, v117
	global_store_dwordx4 v[122:123], v[124:127], off sc0 sc1
	v_mov_b32_e32 v123, v114
	v_mov_b32_e32 v114, v119
	v_mov_b32_e32 v119, v116
	v_mov_b32_e32 v116, v121
	v_mov_b32_e32 v122, v118
	v_pk_mul_f32 v[114:115], v[114:115], v[114:115]
	v_mov_b32_e32 v118, v120
	v_pk_mul_f32 v[116:117], v[116:117], v[116:117]
	v_pk_fma_f32 v[114:115], v[122:123], v[122:123], v[114:115]
	v_pk_fma_f32 v[116:117], v[118:119], v[118:119], v[116:117]
	s_nop 0
	v_pk_add_f32 v[114:115], v[114:115], v[116:117]
	s_nop 0
	v_add_f32_e32 v114, v114, v115
	v_add_f32_e32 v154, v154, v114

; __device__ __forceinline__ u32x4 pack8(f32x4 a, f32x4 b) { u32x4 w; w.x = pk2(a[0], a[1]); w.y = pk2(a[2], a[3]); w.z = pk2(b[0], b[1]); w.w = pk2(b[2], b[3]); return w; }
;     __device__ __forceinline__ void operator()(const f32x4 (&acc)[2][2][4][2], const Unit& un, int wr, int wc, int fr, int fq, int lane) const {
;     ...
;                 const int row = un.pm * 256 + ai * 128 + wr * 64 + m * 16 + fr; float ss = 0.f;
; #pragma unroll
;                 for (int bj = 0; bj < 2; ++bj) {
;                     const size_t off = (size_t)row * DM + c0 + bj * 128; const u32x4 xw = *(const u32x4*)(xb + off);
;                     const f32x4 o0 = (f32x4){bflo(xw.x), bfhi(xw.x), bflo(xw.y), bfhi(xw.y)} + acc[ai][bj][m][0], o1 = (f32x4){bflo(xw.z), bfhi(xw.z), bflo(xw.w), bfhi(xw.w)} + acc[ai][bj][m][1];
;                     if (out) { *(f32x4*)(out + off) = o0; *(f32x4*)(out + off + 4) = o1; }
;                     else { *(u32x4*)(xb + off) = pack8(o0, o1);
;                         ss += ((o0[0] * o0[0] + o0[1] * o0[1]) + (o0[2] * o0[2] + o0[3] * o0[3])) + ((o1[0] * o1[0] + o1[1] * o1[1]) + (o1[2] * o1[2] + o1[3] * o1[3])); }
;                 }
;                 if (!out) { ss += __shfl_xor(ss, 16); ss += __shfl_xor(ss, 32); if (fq == 0) ssqx[(size_t)row * 32 + un.pn * 4 + wc] = ss; }
.LBB0_1372:
	v_or_b32_e32 v114, 16, v142
	s_waitcnt lgkmcnt(0)
	v_ashrrev_i32_e32 v115, 31, v114
	v_lshlrev_b64 v[116:117], 11, v[114:115]
	v_lshl_add_u64 v[118:119], v[116:117], 0, v[140:141]
	v_lshl_add_u64 v[120:121], v[118:119], 1, s[0:1]
	s_mov_b64 s[30:31], -1
	s_and_b64 vcc, exec, s[42:43]
	v_lshlrev_b32_e32 v116, 16, v162
	v_and_b32_e32 v117, 0xffff0000, v162
	v_lshlrev_b32_e32 v122, 16, v163
	v_and_b32_e32 v123, 0xffff0000, v163
	v_pk_add_f32 v[112:113], v[112:113], v[122:123]
	v_pk_add_f32 v[110:111], v[110:111], v[116:117]
	v_lshlrev_b32_e32 v116, 16, v164
	v_and_b32_e32 v117, 0xffff0000, v164
	v_lshlrev_b32_e32 v122, 16, v165
	v_and_b32_e32 v123, 0xffff0000, v165
	v_pk_add_f32 v[108:109], v[108:109], v[122:123]
	v_pk_add_f32 v[106:107], v[106:107], v[116:117]
	v_lshl_add_u64 v[116:117], v[118:119], 2, s[24:25]
	s_cbranch_vccnz .LBB0_1374
	s_mov_b64 s[30:31], 0
	global_store_dwordx4 v[116:117], v[110:113], off sc0 sc1
	global_store_dwordx4 v[116:117], v[106:109], off offset:16 sc0 sc1
.LBB0_1374:
	s_andn2_b64 vcc, exec, s[30:31]
	v_mov_b32_e32 v122, 0
	s_cbranch_vccnz .LBB0_1376
	v_cvt_pk_bf16_f32 v122, v110, v111
	v_cvt_pk_bf16_f32 v123, v112, v113
	v_cvt_pk_bf16_f32 v124, v106, v107
	v_cvt_pk_bf16_f32 v125, v108, v109
	global_store_dwordx4 v[120:121], v[122:125], off sc0 sc1
	v_mov_b32_e32 v121, v106
	v_mov_b32_e32 v106, v111
	v_mov_b32_e32 v111, v108
	v_mov_b32_e32 v108, v113
	v_mov_b32_e32 v120, v110
	v_pk_mul_f32 v[106:107], v[106:107], v[106:107]
	v_mov_b32_e32 v110, v112
	v_pk_mul_f32 v[108:109], v[108:109], v[108:109]
	v_pk_fma_f32 v[106:107], v[120:121], v[120:121], v[106:107]
	v_pk_fma_f32 v[108:109], v[110:111], v[110:111], v[108:109]
	s_nop 0
	v_pk_add_f32 v[106:107], v[106:107], v[108:109]
	s_nop 0
	v_add_f32_e32 v122, v106, v107

; __device__ __forceinline__ u32x4 pack8(f32x4 a, f32x4 b) { u32x4 w; w.x = pk2(a[0], a[1]); w.y = pk2(a[2], a[3]); w.z = pk2(b[0], b[1]); w.w = pk2(b[2], b[3]); return w; }
;     __device__ __forceinline__ void operator()(const f32x4 (&acc)[2][2][4][2], const Unit& un, int wr, int wc, int fr, int fq, int lane) const {
;     ...
;                 const int row = un.pm * 256 + ai * 128 + wr * 64 + m * 16 + fr; float ss = 0.f;
; #pragma unroll
;                 for (int bj = 0; bj < 2; ++bj) {
;                     const size_t off = (size_t)row * DM + c0 + bj * 128; const u32x4 xw = *(const u32x4*)(xb + off);
;                     const f32x4 o0 = (f32x4){bflo(xw.x), bfhi(xw.x), bflo(xw.y), bfhi(xw.y)} + acc[ai][bj][m][0], o1 = (f32x4){bflo(xw.z), bfhi(xw.z), bflo(xw.w), bfhi(xw.w)} + acc[ai][bj][m][1];
;                     if (out) { *(f32x4*)(out + off) = o0; *(f32x4*)(out + off + 4) = o1; }
;                     else { *(u32x4*)(xb + off) = pack8(o0, o1);
;                         ss += ((o0[0] * o0[0] + o0[1] * o0[1]) + (o0[2] * o0[2] + o0[3] * o0[3])) + ((o1[0] * o1[0] + o1[1] * o1[1]) + (o1[2] * o1[2] + o1[3] * o1[3])); }
;                 }
;                 if (!out) { ss += __shfl_xor(ss, 16); ss += __shfl_xor(ss, 32); if (fq == 0) ssqx[(size_t)row * 32 + un.pn * 4 + wc] = ss; }
.LBB0_1379:
	global_store_dwordx4 v[116:117], v[102:105], off offset:512 sc0 sc1
	global_store_dwordx4 v[116:117], v[98:101], off offset:528 sc0 sc1
	s_cbranch_execnz .LBB0_1378
.LBB0_1380:
	v_cvt_pk_bf16_f32 v108, v102, v103
	v_cvt_pk_bf16_f32 v109, v104, v105
	v_cvt_pk_bf16_f32 v110, v98, v99
	v_cvt_pk_bf16_f32 v111, v100, v101
	global_store_dwordx4 v[106:107], v[108:111], off sc0 sc1
	v_mov_b32_e32 v107, v98
	v_mov_b32_e32 v98, v103
	v_mov_b32_e32 v103, v100
	v_mov_b32_e32 v100, v105
	v_mov_b32_e32 v106, v102
	v_pk_mul_f32 v[98:99], v[98:99], v[98:99]
	v_mov_b32_e32 v102, v104
	v_pk_mul_f32 v[100:101], v[100:101], v[100:101]
	v_pk_fma_f32 v[98:99], v[106:107], v[106:107], v[98:99]
	v_pk_fma_f32 v[100:101], v[102:103], v[102:103], v[100:101]
	s_nop 0
	v_pk_add_f32 v[98:99], v[98:99], v[100:101]
	s_nop 0
	v_add_f32_e32 v98, v98, v99
	v_add_f32_e32 v122, v122, v98
	s_and_b64 vcc, exec, s[44:45]
	s_cbranch_vccnz .LBB0_1384

; __device__ __forceinline__ u32x4 pack8(f32x4 a, f32x4 b) { u32x4 w; w.x = pk2(a[0], a[1]); w.y = pk2(a[2], a[3]); w.z = pk2(b[0], b[1]); w.w = pk2(b[2], b[3]); return w; }
;     __device__ __forceinline__ void operator()(const f32x4 (&acc)[2][2][4][2], const Unit& un, int wr, int wc, int fr, int fq, int lane) const {
;     ...
;                 const int row = un.pm * 256 + ai * 128 + wr * 64 + m * 16 + fr; float ss = 0.f;
; #pragma unroll
;                 for (int bj = 0; bj < 2; ++bj) {
;                     const size_t off = (size_t)row * DM + c0 + bj * 128; const u32x4 xw = *(const u32x4*)(xb + off);
;                     const f32x4 o0 = (f32x4){bflo(xw.x), bfhi(xw.x), bflo(xw.y), bfhi(xw.y)} + acc[ai][bj][m][0], o1 = (f32x4){bflo(xw.z), bfhi(xw.z), bflo(xw.w), bfhi(xw.w)} + acc[ai][bj][m][1];
;                     if (out) { *(f32x4*)(out + off) = o0; *(f32x4*)(out + off + 4) = o1; }
;                     else { *(u32x4*)(xb + off) = pack8(o0, o1);
;                         ss += ((o0[0] * o0[0] + o0[1] * o0[1]) + (o0[2] * o0[2] + o0[3] * o0[3])) + ((o1[0] * o1[0] + o1[1] * o1[1]) + (o1[2] * o1[2] + o1[3] * o1[3])); }
;                 }
;                 if (!out) { ss += __shfl_xor(ss, 16); ss += __shfl_xor(ss, 32); if (fq == 0) ssqx[(size_t)row * 32 + un.pn * 4 + wc] = ss; }
.LBB0_1384:
	v_or_b32_e32 v98, 32, v142
	s_waitcnt lgkmcnt(0)
	v_ashrrev_i32_e32 v99, 31, v98
	v_lshlrev_b64 v[100:101], 11, v[98:99]
	v_lshl_add_u64 v[102:103], v[100:101], 0, v[140:141]
	v_lshl_add_u64 v[104:105], v[102:103], 1, s[0:1]
	s_mov_b64 s[30:31], -1
	s_and_b64 vcc, exec, s[42:43]
	v_lshlrev_b32_e32 v100, 16, v170
	v_and_b32_e32 v101, 0xffff0000, v170
	v_lshlrev_b32_e32 v106, 16, v171
	v_and_b32_e32 v107, 0xffff0000, v171
	v_pk_add_f32 v[96:97], v[96:97], v[106:107]
	v_pk_add_f32 v[94:95], v[94:95], v[100:101]
	v_lshlrev_b32_e32 v100, 16, v172
	v_and_b32_e32 v101, 0xffff0000, v172
	v_lshlrev_b32_e32 v106, 16, v173
	v_and_b32_e32 v107, 0xffff0000, v173
	v_pk_add_f32 v[92:93], v[92:93], v[106:107]
	v_pk_add_f32 v[90:91], v[90:91], v[100:101]
	v_lshl_add_u64 v[100:101], v[102:103], 2, s[24:25]
	s_cbranch_vccnz .LBB0_1386
	s_mov_b64 s[30:31], 0
	global_store_dwordx4 v[100:101], v[94:97], off sc0 sc1
	global_store_dwordx4 v[100:101], v[90:93], off offset:16 sc0 sc1
.LBB0_1386:
	s_andn2_b64 vcc, exec, s[30:31]
	v_mov_b32_e32 v106, 0
	s_cbranch_vccnz .LBB0_1388
	v_cvt_pk_bf16_f32 v106, v94, v95
	v_cvt_pk_bf16_f32 v107, v96, v97
	v_cvt_pk_bf16_f32 v108, v90, v91
	v_cvt_pk_bf16_f32 v109, v92, v93
	global_store_dwordx4 v[104:105], v[106:109], off sc0 sc1
	v_mov_b32_e32 v105, v90
	v_mov_b32_e32 v90, v95
	v_mov_b32_e32 v95, v92
	v_mov_b32_e32 v92, v97
	v_mov_b32_e32 v104, v94
	v_pk_mul_f32 v[90:91], v[90:91], v[90:91]
	v_mov_b32_e32 v94, v96
	v_pk_mul_f32 v[92:93], v[92:93], v[92:93]
	v_pk_fma_f32 v[90:91], v[104:105], v[104:105], v[90:91]
	v_pk_fma_f32 v[92:93], v[94:95], v[94:95], v[92:93]
	s_nop 0
	v_pk_add_f32 v[90:91], v[90:91], v[92:93]
	s_nop 0
	v_add_f32_e32 v106, v90, v91

; __device__ __forceinline__ u32x4 pack8(f32x4 a, f32x4 b) { u32x4 w; w.x = pk2(a[0], a[1]); w.y = pk2(a[2], a[3]); w.z = pk2(b[0], b[1]); w.w = pk2(b[2], b[3]); return w; }
;     __device__ __forceinline__ void operator()(const f32x4 (&acc)[2][2][4][2], const Unit& un, int wr, int wc, int fr, int fq, int lane) const {
;     ...
;                 const int row = un.pm * 256 + ai * 128 + wr * 64 + m * 16 + fr; float ss = 0.f;
; #pragma unroll
;                 for (int bj = 0; bj < 2; ++bj) {
;                     const size_t off = (size_t)row * DM + c0 + bj * 128; const u32x4 xw = *(const u32x4*)(xb + off);
;                     const f32x4 o0 = (f32x4){bflo(xw.x), bfhi(xw.x), bflo(xw.y), bfhi(xw.y)} + acc[ai][bj][m][0], o1 = (f32x4){bflo(xw.z), bfhi(xw.z), bflo(xw.w), bfhi(xw.w)} + acc[ai][bj][m][1];
;                     if (out) { *(f32x4*)(out + off) = o0; *(f32x4*)(out + off + 4) = o1; }
;                     else { *(u32x4*)(xb + off) = pack8(o0, o1);
;                         ss += ((o0[0] * o0[0] + o0[1] * o0[1]) + (o0[2] * o0[2] + o0[3] * o0[3])) + ((o1[0] * o1[0] + o1[1] * o1[1]) + (o1[2] * o1[2] + o1[3] * o1[3])); }
;                 }
;                 if (!out) { ss += __shfl_xor(ss, 16); ss += __shfl_xor(ss, 32); if (fq == 0) ssqx[(size_t)row * 32 + un.pn * 4 + wc] = ss; }
.LBB0_1391:
	global_store_dwordx4 v[100:101], v[86:89], off offset:512 sc0 sc1
	global_store_dwordx4 v[100:101], v[82:85], off offset:528 sc0 sc1
	s_cbranch_execnz .LBB0_1390
.LBB0_1392:
	v_cvt_pk_bf16_f32 v92, v86, v87
	v_cvt_pk_bf16_f32 v93, v88, v89
	v_cvt_pk_bf16_f32 v94, v82, v83
	v_cvt_pk_bf16_f32 v95, v84, v85
	global_store_dwordx4 v[90:91], v[92:95], off sc0 sc1
	v_mov_b32_e32 v91, v82
	v_mov_b32_e32 v82, v87
	v_mov_b32_e32 v87, v84
	v_mov_b32_e32 v84, v89
	v_mov_b32_e32 v90, v86
	v_pk_mul_f32 v[82:83], v[82:83], v[82:83]
	v_mov_b32_e32 v86, v88
	v_pk_mul_f32 v[84:85], v[84:85], v[84:85]
	v_pk_fma_f32 v[82:83], v[90:91], v[90:91], v[82:83]
	v_pk_fma_f32 v[84:85], v[86:87], v[86:87], v[84:85]
	s_nop 0
	v_pk_add_f32 v[82:83], v[82:83], v[84:85]
	s_nop 0
	v_add_f32_e32 v82, v82, v83
	v_add_f32_e32 v106, v106, v82
	s_and_b64 vcc, exec, s[44:45]
	s_cbranch_vccnz .LBB0_1396

; __device__ __forceinline__ u32x4 pack8(f32x4 a, f32x4 b) { u32x4 w; w.x = pk2(a[0], a[1]); w.y = pk2(a[2], a[3]); w.z = pk2(b[0], b[1]); w.w = pk2(b[2], b[3]); return w; }
;     __device__ __forceinline__ void operator()(const f32x4 (&acc)[2][2][4][2], const Unit& un, int wr, int wc, int fr, int fq, int lane) const {
;     ...
;                 const int row = un.pm * 256 + ai * 128 + wr * 64 + m * 16 + fr; float ss = 0.f;
; #pragma unroll
;                 for (int bj = 0; bj < 2; ++bj) {
;                     const size_t off = (size_t)row * DM + c0 + bj * 128; const u32x4 xw = *(const u32x4*)(xb + off);
;                     const f32x4 o0 = (f32x4){bflo(xw.x), bfhi(xw.x), bflo(xw.y), bfhi(xw.y)} + acc[ai][bj][m][0], o1 = (f32x4){bflo(xw.z), bfhi(xw.z), bflo(xw.w), bfhi(xw.w)} + acc[ai][bj][m][1];
;                     if (out) { *(f32x4*)(out + off) = o0; *(f32x4*)(out + off + 4) = o1; }
;                     else { *(u32x4*)(xb + off) = pack8(o0, o1);
;                         ss += ((o0[0] * o0[0] + o0[1] * o0[1]) + (o0[2] * o0[2] + o0[3] * o0[3])) + ((o1[0] * o1[0] + o1[1] * o1[1]) + (o1[2] * o1[2] + o1[3] * o1[3])); }
;                 }
;                 if (!out) { ss += __shfl_xor(ss, 16); ss += __shfl_xor(ss, 32); if (fq == 0) ssqx[(size_t)row * 32 + un.pn * 4 + wc] = ss; }
.LBB0_1396:
	v_or_b32_e32 v82, 48, v142
	s_waitcnt lgkmcnt(0)
	v_ashrrev_i32_e32 v83, 31, v82
	v_lshlrev_b64 v[84:85], 11, v[82:83]
	v_lshl_add_u64 v[86:87], v[84:85], 0, v[140:141]
	v_lshl_add_u64 v[88:89], v[86:87], 1, s[0:1]
	s_mov_b64 s[30:31], -1
	s_and_b64 vcc, exec, s[42:43]
	v_lshlrev_b32_e32 v84, 16, v178
	v_and_b32_e32 v85, 0xffff0000, v178
	v_lshlrev_b32_e32 v90, 16, v179
	v_and_b32_e32 v91, 0xffff0000, v179
	v_pk_add_f32 v[80:81], v[80:81], v[90:91]
	v_pk_add_f32 v[78:79], v[78:79], v[84:85]
	v_lshlrev_b32_e32 v84, 16, v180
	v_and_b32_e32 v85, 0xffff0000, v180
	v_lshlrev_b32_e32 v90, 16, v181
	v_and_b32_e32 v91, 0xffff0000, v181
	v_pk_add_f32 v[76:77], v[76:77], v[90:91]
	v_pk_add_f32 v[74:75], v[74:75], v[84:85]
	v_lshl_add_u64 v[84:85], v[86:87], 2, s[24:25]
	s_cbranch_vccnz .LBB0_1398
	s_mov_b64 s[30:31], 0
	global_store_dwordx4 v[84:85], v[78:81], off sc0 sc1
	global_store_dwordx4 v[84:85], v[74:77], off offset:16 sc0 sc1
.LBB0_1398:
	s_andn2_b64 vcc, exec, s[30:31]
	v_mov_b32_e32 v90, 0
	s_cbranch_vccnz .LBB0_1400
	v_cvt_pk_bf16_f32 v90, v78, v79
	v_cvt_pk_bf16_f32 v91, v80, v81
	v_cvt_pk_bf16_f32 v92, v74, v75
	v_cvt_pk_bf16_f32 v93, v76, v77
	global_store_dwordx4 v[88:89], v[90:93], off sc0 sc1
	v_mov_b32_e32 v89, v74
	v_mov_b32_e32 v74, v79
	v_mov_b32_e32 v79, v76
	v_mov_b32_e32 v76, v81
	v_mov_b32_e32 v88, v78
	v_pk_mul_f32 v[74:75], v[74:75], v[74:75]
	v_mov_b32_e32 v78, v80
	v_pk_mul_f32 v[76:77], v[76:77], v[76:77]
	v_pk_fma_f32 v[74:75], v[88:89], v[88:89], v[74:75]
	v_pk_fma_f32 v[76:77], v[78:79], v[78:79], v[76:77]
	s_nop 0
	v_pk_add_f32 v[74:75], v[74:75], v[76:77]
	s_nop 0
	v_add_f32_e32 v90, v74, v75

; __device__ __forceinline__ u32x4 pack8(f32x4 a, f32x4 b) { u32x4 w; w.x = pk2(a[0], a[1]); w.y = pk2(a[2], a[3]); w.z = pk2(b[0], b[1]); w.w = pk2(b[2], b[3]); return w; }
;     __device__ __forceinline__ void operator()(const f32x4 (&acc)[2][2][4][2], const Unit& un, int wr, int wc, int fr, int fq, int lane) const {
;     ...
;                 const int row = un.pm * 256 + ai * 128 + wr * 64 + m * 16 + fr; float ss = 0.f;
; #pragma unroll
;                 for (int bj = 0; bj < 2; ++bj) {
;                     const size_t off = (size_t)row * DM + c0 + bj * 128; const u32x4 xw = *(const u32x4*)(xb + off);
;                     const f32x4 o0 = (f32x4){bflo(xw.x), bfhi(xw.x), bflo(xw.y), bfhi(xw.y)} + acc[ai][bj][m][0], o1 = (f32x4){bflo(xw.z), bfhi(xw.z), bflo(xw.w), bfhi(xw.w)} + acc[ai][bj][m][1];
;                     if (out) { *(f32x4*)(out + off) = o0; *(f32x4*)(out + off + 4) = o1; }
;                     else { *(u32x4*)(xb + off) = pack8(o0, o1);
;                         ss += ((o0[0] * o0[0] + o0[1] * o0[1]) + (o0[2] * o0[2] + o0[3] * o0[3])) + ((o1[0] * o1[0] + o1[1] * o1[1]) + (o1[2] * o1[2] + o1[3] * o1[3])); }
;                 }
;                 if (!out) { ss += __shfl_xor(ss, 16); ss += __shfl_xor(ss, 32); if (fq == 0) ssqx[(size_t)row * 32 + un.pn * 4 + wc] = ss; }
.LBB0_1403:
	global_store_dwordx4 v[84:85], v[70:73], off offset:512 sc0 sc1
	global_store_dwordx4 v[84:85], v[66:69], off offset:528 sc0 sc1
	s_cbranch_execnz .LBB0_1402
.LBB0_1404:
	v_cvt_pk_bf16_f32 v76, v70, v71
	v_cvt_pk_bf16_f32 v77, v72, v73
	v_cvt_pk_bf16_f32 v78, v66, v67
	v_cvt_pk_bf16_f32 v79, v68, v69
	global_store_dwordx4 v[74:75], v[76:79], off sc0 sc1
	v_mov_b32_e32 v75, v66
	v_mov_b32_e32 v66, v71
	v_mov_b32_e32 v71, v68
	v_mov_b32_e32 v68, v73
	v_mov_b32_e32 v74, v70
	v_pk_mul_f32 v[66:67], v[66:67], v[66:67]
	v_mov_b32_e32 v70, v72
	v_pk_mul_f32 v[68:69], v[68:69], v[68:69]
	v_pk_fma_f32 v[66:67], v[74:75], v[74:75], v[66:67]
	v_pk_fma_f32 v[68:69], v[70:71], v[70:71], v[68:69]
	s_nop 0
	v_pk_add_f32 v[66:67], v[66:67], v[68:69]
	s_nop 0
	v_add_f32_e32 v66, v66, v67
	v_add_f32_e32 v90, v90, v66
	s_and_b64 vcc, exec, s[44:45]
	s_cbranch_vccnz .LBB0_1408

; __device__ __forceinline__ u32x4 pack8(f32x4 a, f32x4 b) { u32x4 w; w.x = pk2(a[0], a[1]); w.y = pk2(a[2], a[3]); w.z = pk2(b[0], b[1]); w.w = pk2(b[2], b[3]); return w; }
;     __device__ __forceinline__ void operator()(const f32x4 (&acc)[2][2][4][2], const Unit& un, int wr, int wc, int fr, int fq, int lane) const {
;     ...
;                 const int row = un.pm * 256 + ai * 128 + wr * 64 + m * 16 + fr; float ss = 0.f;
; #pragma unroll
;                 for (int bj = 0; bj < 2; ++bj) {
;                     const size_t off = (size_t)row * DM + c0 + bj * 128; const u32x4 xw = *(const u32x4*)(xb + off);
;                     const f32x4 o0 = (f32x4){bflo(xw.x), bfhi(xw.x), bflo(xw.y), bfhi(xw.y)} + acc[ai][bj][m][0], o1 = (f32x4){bflo(xw.z), bfhi(xw.z), bflo(xw.w), bfhi(xw.w)} + acc[ai][bj][m][1];
;                     if (out) { *(f32x4*)(out + off) = o0; *(f32x4*)(out + off + 4) = o1; }
;                     else { *(u32x4*)(xb + off) = pack8(o0, o1);
;                         ss += ((o0[0] * o0[0] + o0[1] * o0[1]) + (o0[2] * o0[2] + o0[3] * o0[3])) + ((o1[0] * o1[0] + o1[1] * o1[1]) + (o1[2] * o1[2] + o1[3] * o1[3])); }
;                 }
;                 if (!out) { ss += __shfl_xor(ss, 16); ss += __shfl_xor(ss, 32); if (fq == 0) ssqx[(size_t)row * 32 + un.pn * 4 + wc] = ss; }
.LBB0_1408:
	v_add_u32_e32 v66, 0x80, v142
	s_waitcnt lgkmcnt(0)
	v_ashrrev_i32_e32 v67, 31, v66
	v_lshlrev_b64 v[68:69], 11, v[66:67]
	v_lshl_add_u64 v[70:71], v[68:69], 0, v[140:141]
	v_lshl_add_u64 v[72:73], v[70:71], 1, s[0:1]
	s_mov_b64 s[30:31], -1
	s_and_b64 vcc, exec, s[42:43]
	v_lshlrev_b32_e32 v68, 16, v186
	v_and_b32_e32 v69, 0xffff0000, v186
	v_lshlrev_b32_e32 v74, 16, v187
	v_and_b32_e32 v75, 0xffff0000, v187
	v_pk_add_f32 v[64:65], v[64:65], v[74:75]
	v_pk_add_f32 v[62:63], v[62:63], v[68:69]
	v_lshlrev_b32_e32 v68, 16, v188
	v_and_b32_e32 v69, 0xffff0000, v188
	v_lshlrev_b32_e32 v74, 16, v189
	v_and_b32_e32 v75, 0xffff0000, v189
	v_pk_add_f32 v[60:61], v[60:61], v[74:75]
	v_pk_add_f32 v[58:59], v[58:59], v[68:69]
	v_lshl_add_u64 v[68:69], v[70:71], 2, s[24:25]
	s_cbranch_vccnz .LBB0_1410
	s_mov_b64 s[30:31], 0
	global_store_dwordx4 v[68:69], v[62:65], off sc0 sc1
	global_store_dwordx4 v[68:69], v[58:61], off offset:16 sc0 sc1
.LBB0_1410:
	s_andn2_b64 vcc, exec, s[30:31]
	v_mov_b32_e32 v74, 0
	s_cbranch_vccnz .LBB0_1412
	v_cvt_pk_bf16_f32 v74, v62, v63
	v_cvt_pk_bf16_f32 v75, v64, v65
	v_cvt_pk_bf16_f32 v76, v58, v59
	v_cvt_pk_bf16_f32 v77, v60, v61
	global_store_dwordx4 v[72:73], v[74:77], off sc0 sc1
	v_mov_b32_e32 v73, v58
	v_mov_b32_e32 v58, v63
	v_mov_b32_e32 v63, v60
	v_mov_b32_e32 v60, v65
	v_mov_b32_e32 v72, v62
	v_pk_mul_f32 v[58:59], v[58:59], v[58:59]
	v_mov_b32_e32 v62, v64
	v_pk_mul_f32 v[60:61], v[60:61], v[60:61]
	v_pk_fma_f32 v[58:59], v[72:73], v[72:73], v[58:59]
	v_pk_fma_f32 v[60:61], v[62:63], v[62:63], v[60:61]
	s_nop 0
	v_pk_add_f32 v[58:59], v[58:59], v[60:61]
	s_nop 0
	v_add_f32_e32 v74, v58, v59

; __device__ __forceinline__ u32x4 pack8(f32x4 a, f32x4 b) { u32x4 w; w.x = pk2(a[0], a[1]); w.y = pk2(a[2], a[3]); w.z = pk2(b[0], b[1]); w.w = pk2(b[2], b[3]); return w; }
;     __device__ __forceinline__ void operator()(const f32x4 (&acc)[2][2][4][2], const Unit& un, int wr, int wc, int fr, int fq, int lane) const {
;     ...
;                 const int row = un.pm * 256 + ai * 128 + wr * 64 + m * 16 + fr; float ss = 0.f;
; #pragma unroll
;                 for (int bj = 0; bj < 2; ++bj) {
;                     const size_t off = (size_t)row * DM + c0 + bj * 128; const u32x4 xw = *(const u32x4*)(xb + off);
;                     const f32x4 o0 = (f32x4){bflo(xw.x), bfhi(xw.x), bflo(xw.y), bfhi(xw.y)} + acc[ai][bj][m][0], o1 = (f32x4){bflo(xw.z), bfhi(xw.z), bflo(xw.w), bfhi(xw.w)} + acc[ai][bj][m][1];
;                     if (out) { *(f32x4*)(out + off) = o0; *(f32x4*)(out + off + 4) = o1; }
;                     else { *(u32x4*)(xb + off) = pack8(o0, o1);
;                         ss += ((o0[0] * o0[0] + o0[1] * o0[1]) + (o0[2] * o0[2] + o0[3] * o0[3])) + ((o1[0] * o1[0] + o1[1] * o1[1]) + (o1[2] * o1[2] + o1[3] * o1[3])); }
;                 }
;                 if (!out) { ss += __shfl_xor(ss, 16); ss += __shfl_xor(ss, 32); if (fq == 0) ssqx[(size_t)row * 32 + un.pn * 4 + wc] = ss; }
.LBB0_1415:
	global_store_dwordx4 v[68:69], v[54:57], off offset:512 sc0 sc1
	global_store_dwordx4 v[68:69], v[50:53], off offset:528 sc0 sc1
	s_cbranch_execnz .LBB0_1414
.LBB0_1416:
	v_cvt_pk_bf16_f32 v60, v54, v55
	v_cvt_pk_bf16_f32 v61, v56, v57
	v_cvt_pk_bf16_f32 v62, v50, v51
	v_cvt_pk_bf16_f32 v63, v52, v53
	global_store_dwordx4 v[58:59], v[60:63], off sc0 sc1
	v_mov_b32_e32 v59, v50
	v_mov_b32_e32 v50, v55
	v_mov_b32_e32 v55, v52
	v_mov_b32_e32 v52, v57
	v_mov_b32_e32 v58, v54
	v_pk_mul_f32 v[50:51], v[50:51], v[50:51]
	v_mov_b32_e32 v54, v56
	v_pk_mul_f32 v[52:53], v[52:53], v[52:53]
	v_pk_fma_f32 v[50:51], v[58:59], v[58:59], v[50:51]
	v_pk_fma_f32 v[52:53], v[54:55], v[54:55], v[52:53]
	s_nop 0
	v_pk_add_f32 v[50:51], v[50:51], v[52:53]
	s_nop 0
	v_add_f32_e32 v50, v50, v51
	v_add_f32_e32 v74, v74, v50
	s_and_b64 vcc, exec, s[44:45]
	s_cbranch_vccnz .LBB0_1420

; __device__ __forceinline__ u32x4 pack8(f32x4 a, f32x4 b) { u32x4 w; w.x = pk2(a[0], a[1]); w.y = pk2(a[2], a[3]); w.z = pk2(b[0], b[1]); w.w = pk2(b[2], b[3]); return w; }
;     __device__ __forceinline__ void operator()(const f32x4 (&acc)[2][2][4][2], const Unit& un, int wr, int wc, int fr, int fq, int lane) const {
;     ...
;                 const int row = un.pm * 256 + ai * 128 + wr * 64 + m * 16 + fr; float ss = 0.f;
; #pragma unroll
;                 for (int bj = 0; bj < 2; ++bj) {
;                     const size_t off = (size_t)row * DM + c0 + bj * 128; const u32x4 xw = *(const u32x4*)(xb + off);
;                     const f32x4 o0 = (f32x4){bflo(xw.x), bfhi(xw.x), bflo(xw.y), bfhi(xw.y)} + acc[ai][bj][m][0], o1 = (f32x4){bflo(xw.z), bfhi(xw.z), bflo(xw.w), bfhi(xw.w)} + acc[ai][bj][m][1];
;                     if (out) { *(f32x4*)(out + off) = o0; *(f32x4*)(out + off + 4) = o1; }
;                     else { *(u32x4*)(xb + off) = pack8(o0, o1);
;                         ss += ((o0[0] * o0[0] + o0[1] * o0[1]) + (o0[2] * o0[2] + o0[3] * o0[3])) + ((o1[0] * o1[0] + o1[1] * o1[1]) + (o1[2] * o1[2] + o1[3] * o1[3])); }
;                 }
;                 if (!out) { ss += __shfl_xor(ss, 16); ss += __shfl_xor(ss, 32); if (fq == 0) ssqx[(size_t)row * 32 + un.pn * 4 + wc] = ss; }
.LBB0_1420:
	v_add_u32_e32 v50, 0x90, v142
	s_waitcnt lgkmcnt(0)
	v_ashrrev_i32_e32 v51, 31, v50
	v_lshlrev_b64 v[52:53], 11, v[50:51]
	v_lshl_add_u64 v[54:55], v[52:53], 0, v[140:141]
	v_lshl_add_u64 v[56:57], v[54:55], 1, s[0:1]
	s_mov_b64 s[30:31], -1
	s_and_b64 vcc, exec, s[42:43]
	v_lshlrev_b32_e32 v52, 16, v194
	v_and_b32_e32 v53, 0xffff0000, v194
	v_lshlrev_b32_e32 v58, 16, v195
	v_and_b32_e32 v59, 0xffff0000, v195
	v_pk_add_f32 v[48:49], v[48:49], v[58:59]
	v_pk_add_f32 v[46:47], v[46:47], v[52:53]
	v_lshlrev_b32_e32 v52, 16, v196
	v_and_b32_e32 v53, 0xffff0000, v196
	v_lshlrev_b32_e32 v58, 16, v197
	v_and_b32_e32 v59, 0xffff0000, v197
	v_pk_add_f32 v[44:45], v[44:45], v[58:59]
	v_pk_add_f32 v[42:43], v[42:43], v[52:53]
	v_lshl_add_u64 v[52:53], v[54:55], 2, s[24:25]
	s_cbranch_vccnz .LBB0_1422
	s_mov_b64 s[30:31], 0
	global_store_dwordx4 v[52:53], v[46:49], off sc0 sc1
	global_store_dwordx4 v[52:53], v[42:45], off offset:16 sc0 sc1
.LBB0_1422:
	s_andn2_b64 vcc, exec, s[30:31]
	v_mov_b32_e32 v58, 0
	s_cbranch_vccnz .LBB0_1424
	v_cvt_pk_bf16_f32 v58, v46, v47
	v_cvt_pk_bf16_f32 v59, v48, v49
	v_cvt_pk_bf16_f32 v60, v42, v43
	v_cvt_pk_bf16_f32 v61, v44, v45
	global_store_dwordx4 v[56:57], v[58:61], off sc0 sc1
	v_mov_b32_e32 v57, v42
	v_mov_b32_e32 v42, v47
	v_mov_b32_e32 v47, v44
	v_mov_b32_e32 v44, v49
	v_mov_b32_e32 v56, v46
	v_pk_mul_f32 v[42:43], v[42:43], v[42:43]
	v_mov_b32_e32 v46, v48
	v_pk_mul_f32 v[44:45], v[44:45], v[44:45]
	v_pk_fma_f32 v[42:43], v[56:57], v[56:57], v[42:43]
	v_pk_fma_f32 v[44:45], v[46:47], v[46:47], v[44:45]
	s_nop 0
	v_pk_add_f32 v[42:43], v[42:43], v[44:45]
	s_nop 0
	v_add_f32_e32 v58, v42, v43

; __device__ __forceinline__ u32x4 pack8(f32x4 a, f32x4 b) { u32x4 w; w.x = pk2(a[0], a[1]); w.y = pk2(a[2], a[3]); w.z = pk2(b[0], b[1]); w.w = pk2(b[2], b[3]); return w; }
;     __device__ __forceinline__ void operator()(const f32x4 (&acc)[2][2][4][2], const Unit& un, int wr, int wc, int fr, int fq, int lane) const {
;     ...
;                 const int row = un.pm * 256 + ai * 128 + wr * 64 + m * 16 + fr; float ss = 0.f;
; #pragma unroll
;                 for (int bj = 0; bj < 2; ++bj) {
;                     const size_t off = (size_t)row * DM + c0 + bj * 128; const u32x4 xw = *(const u32x4*)(xb + off);
;                     const f32x4 o0 = (f32x4){bflo(xw.x), bfhi(xw.x), bflo(xw.y), bfhi(xw.y)} + acc[ai][bj][m][0], o1 = (f32x4){bflo(xw.z), bfhi(xw.z), bflo(xw.w), bfhi(xw.w)} + acc[ai][bj][m][1];
;                     if (out) { *(f32x4*)(out + off) = o0; *(f32x4*)(out + off + 4) = o1; }
;                     else { *(u32x4*)(xb + off) = pack8(o0, o1);
;                         ss += ((o0[0] * o0[0] + o0[1] * o0[1]) + (o0[2] * o0[2] + o0[3] * o0[3])) + ((o1[0] * o1[0] + o1[1] * o1[1]) + (o1[2] * o1[2] + o1[3] * o1[3])); }
;                 }
;                 if (!out) { ss += __shfl_xor(ss, 16); ss += __shfl_xor(ss, 32); if (fq == 0) ssqx[(size_t)row * 32 + un.pn * 4 + wc] = ss; }
.LBB0_1427:
	global_store_dwordx4 v[52:53], v[38:41], off offset:512 sc0 sc1
	global_store_dwordx4 v[52:53], v[34:37], off offset:528 sc0 sc1
	s_cbranch_execnz .LBB0_1426
.LBB0_1428:
	v_cvt_pk_bf16_f32 v44, v38, v39
	v_cvt_pk_bf16_f32 v45, v40, v41
	v_cvt_pk_bf16_f32 v46, v34, v35
	v_cvt_pk_bf16_f32 v47, v36, v37
	global_store_dwordx4 v[42:43], v[44:47], off sc0 sc1
	v_mov_b32_e32 v43, v34
	v_mov_b32_e32 v34, v39
	v_mov_b32_e32 v39, v36
	v_mov_b32_e32 v36, v41
	v_mov_b32_e32 v42, v38
	v_pk_mul_f32 v[34:35], v[34:35], v[34:35]
	v_mov_b32_e32 v38, v40
	v_pk_mul_f32 v[36:37], v[36:37], v[36:37]
	v_pk_fma_f32 v[34:35], v[42:43], v[42:43], v[34:35]
	v_pk_fma_f32 v[36:37], v[38:39], v[38:39], v[36:37]
	s_nop 0
	v_pk_add_f32 v[34:35], v[34:35], v[36:37]
	s_nop 0
	v_add_f32_e32 v34, v34, v35
	v_add_f32_e32 v58, v58, v34
	s_and_b64 vcc, exec, s[44:45]
	s_cbranch_vccnz .LBB0_1432

; __device__ __forceinline__ u32x4 pack8(f32x4 a, f32x4 b) { u32x4 w; w.x = pk2(a[0], a[1]); w.y = pk2(a[2], a[3]); w.z = pk2(b[0], b[1]); w.w = pk2(b[2], b[3]); return w; }
;     __device__ __forceinline__ void operator()(const f32x4 (&acc)[2][2][4][2], const Unit& un, int wr, int wc, int fr, int fq, int lane) const {
;     ...
;                 const int row = un.pm * 256 + ai * 128 + wr * 64 + m * 16 + fr; float ss = 0.f;
; #pragma unroll
;                 for (int bj = 0; bj < 2; ++bj) {
;                     const size_t off = (size_t)row * DM + c0 + bj * 128; const u32x4 xw = *(const u32x4*)(xb + off);
;                     const f32x4 o0 = (f32x4){bflo(xw.x), bfhi(xw.x), bflo(xw.y), bfhi(xw.y)} + acc[ai][bj][m][0], o1 = (f32x4){bflo(xw.z), bfhi(xw.z), bflo(xw.w), bfhi(xw.w)} + acc[ai][bj][m][1];
;                     if (out) { *(f32x4*)(out + off) = o0; *(f32x4*)(out + off + 4) = o1; }
;                     else { *(u32x4*)(xb + off) = pack8(o0, o1);
;                         ss += ((o0[0] * o0[0] + o0[1] * o0[1]) + (o0[2] * o0[2] + o0[3] * o0[3])) + ((o1[0] * o1[0] + o1[1] * o1[1]) + (o1[2] * o1[2] + o1[3] * o1[3])); }
;                 }
;                 if (!out) { ss += __shfl_xor(ss, 16); ss += __shfl_xor(ss, 32); if (fq == 0) ssqx[(size_t)row * 32 + un.pn * 4 + wc] = ss; }
.LBB0_1432:
	v_add_u32_e32 v34, 0xa0, v142
	s_waitcnt lgkmcnt(0)
	v_ashrrev_i32_e32 v35, 31, v34
	v_lshlrev_b64 v[36:37], 11, v[34:35]
	v_lshl_add_u64 v[38:39], v[36:37], 0, v[140:141]
	v_lshl_add_u64 v[40:41], v[38:39], 1, s[0:1]
	s_mov_b64 s[30:31], -1
	s_and_b64 vcc, exec, s[42:43]
	v_lshlrev_b32_e32 v36, 16, v210
	v_and_b32_e32 v37, 0xffff0000, v210
	v_lshlrev_b32_e32 v42, 16, v211
	v_and_b32_e32 v43, 0xffff0000, v211
	v_pk_add_f32 v[32:33], v[32:33], v[42:43]
	v_pk_add_f32 v[30:31], v[30:31], v[36:37]
	v_lshlrev_b32_e32 v36, 16, v212
	v_and_b32_e32 v37, 0xffff0000, v212
	v_lshlrev_b32_e32 v42, 16, v213
	v_and_b32_e32 v43, 0xffff0000, v213
	v_pk_add_f32 v[28:29], v[28:29], v[42:43]
	v_pk_add_f32 v[26:27], v[26:27], v[36:37]
	v_lshl_add_u64 v[36:37], v[38:39], 2, s[24:25]
	s_cbranch_vccnz .LBB0_1434
	s_mov_b64 s[30:31], 0
	global_store_dwordx4 v[36:37], v[30:33], off sc0 sc1
	global_store_dwordx4 v[36:37], v[26:29], off offset:16 sc0 sc1
.LBB0_1434:
	s_andn2_b64 vcc, exec, s[30:31]
	v_mov_b32_e32 v42, 0
	s_cbranch_vccnz .LBB0_1436
	v_cvt_pk_bf16_f32 v42, v30, v31
	v_cvt_pk_bf16_f32 v43, v32, v33
	v_cvt_pk_bf16_f32 v44, v26, v27
	v_cvt_pk_bf16_f32 v45, v28, v29
	global_store_dwordx4 v[40:41], v[42:45], off sc0 sc1
	v_mov_b32_e32 v41, v26
	v_mov_b32_e32 v26, v31
	v_mov_b32_e32 v31, v28
	v_mov_b32_e32 v28, v33
	v_mov_b32_e32 v40, v30
	v_pk_mul_f32 v[26:27], v[26:27], v[26:27]
	v_mov_b32_e32 v30, v32
	v_pk_mul_f32 v[28:29], v[28:29], v[28:29]
	v_pk_fma_f32 v[26:27], v[40:41], v[40:41], v[26:27]
	v_pk_fma_f32 v[28:29], v[30:31], v[30:31], v[28:29]
	s_nop 0
	v_pk_add_f32 v[26:27], v[26:27], v[28:29]
	s_nop 0
	v_add_f32_e32 v42, v26, v27

; __device__ __forceinline__ u32x4 pack8(f32x4 a, f32x4 b) { u32x4 w; w.x = pk2(a[0], a[1]); w.y = pk2(a[2], a[3]); w.z = pk2(b[0], b[1]); w.w = pk2(b[2], b[3]); return w; }
;     __device__ __forceinline__ void operator()(const f32x4 (&acc)[2][2][4][2], const Unit& un, int wr, int wc, int fr, int fq, int lane) const {
;     ...
;                 const int row = un.pm * 256 + ai * 128 + wr * 64 + m * 16 + fr; float ss = 0.f;
; #pragma unroll
;                 for (int bj = 0; bj < 2; ++bj) {
;                     const size_t off = (size_t)row * DM + c0 + bj * 128; const u32x4 xw = *(const u32x4*)(xb + off);
;                     const f32x4 o0 = (f32x4){bflo(xw.x), bfhi(xw.x), bflo(xw.y), bfhi(xw.y)} + acc[ai][bj][m][0], o1 = (f32x4){bflo(xw.z), bfhi(xw.z), bflo(xw.w), bfhi(xw.w)} + acc[ai][bj][m][1];
;                     if (out) { *(f32x4*)(out + off) = o0; *(f32x4*)(out + off + 4) = o1; }
;                     else { *(u32x4*)(xb + off) = pack8(o0, o1);
;                         ss += ((o0[0] * o0[0] + o0[1] * o0[1]) + (o0[2] * o0[2] + o0[3] * o0[3])) + ((o1[0] * o1[0] + o1[1] * o1[1]) + (o1[2] * o1[2] + o1[3] * o1[3])); }
;                 }
;                 if (!out) { ss += __shfl_xor(ss, 16); ss += __shfl_xor(ss, 32); if (fq == 0) ssqx[(size_t)row * 32 + un.pn * 4 + wc] = ss; }
.LBB0_1439:
	global_store_dwordx4 v[36:37], v[20:23], off offset:512 sc0 sc1
	global_store_dwordx4 v[36:37], v[16:19], off offset:528 sc0 sc1
	s_cbranch_execnz .LBB0_1438
.LBB0_1440:
	v_cvt_pk_bf16_f32 v28, v20, v21
	v_cvt_pk_bf16_f32 v29, v22, v23
	v_cvt_pk_bf16_f32 v30, v16, v17
	v_cvt_pk_bf16_f32 v31, v18, v19
	global_store_dwordx4 v[26:27], v[28:31], off sc0 sc1
	v_mov_b32_e32 v27, v16
	v_mov_b32_e32 v16, v21
	v_mov_b32_e32 v21, v18
	v_mov_b32_e32 v18, v23
	v_mov_b32_e32 v26, v20
	v_pk_mul_f32 v[16:17], v[16:17], v[16:17]
	v_mov_b32_e32 v20, v22
	v_pk_mul_f32 v[18:19], v[18:19], v[18:19]
	v_pk_fma_f32 v[16:17], v[26:27], v[26:27], v[16:17]
	v_pk_fma_f32 v[18:19], v[20:21], v[20:21], v[18:19]
	s_nop 0
	v_pk_add_f32 v[16:17], v[16:17], v[18:19]
	s_nop 0
	v_add_f32_e32 v16, v16, v17
	v_add_f32_e32 v42, v42, v16
	s_and_b64 vcc, exec, s[44:45]
	s_cbranch_vccnz .LBB0_1444

; __device__ __forceinline__ u32x4 pack8(f32x4 a, f32x4 b) { u32x4 w; w.x = pk2(a[0], a[1]); w.y = pk2(a[2], a[3]); w.z = pk2(b[0], b[1]); w.w = pk2(b[2], b[3]); return w; }
;     __device__ __forceinline__ void operator()(const f32x4 (&acc)[2][2][4][2], const Unit& un, int wr, int wc, int fr, int fq, int lane) const {
;     ...
;                 const int row = un.pm * 256 + ai * 128 + wr * 64 + m * 16 + fr; float ss = 0.f;
; #pragma unroll
;                 for (int bj = 0; bj < 2; ++bj) {
;                     const size_t off = (size_t)row * DM + c0 + bj * 128; const u32x4 xw = *(const u32x4*)(xb + off);
;                     const f32x4 o0 = (f32x4){bflo(xw.x), bfhi(xw.x), bflo(xw.y), bfhi(xw.y)} + acc[ai][bj][m][0], o1 = (f32x4){bflo(xw.z), bfhi(xw.z), bflo(xw.w), bfhi(xw.w)} + acc[ai][bj][m][1];
;                     if (out) { *(f32x4*)(out + off) = o0; *(f32x4*)(out + off + 4) = o1; }
;                     else { *(u32x4*)(xb + off) = pack8(o0, o1);
;                         ss += ((o0[0] * o0[0] + o0[1] * o0[1]) + (o0[2] * o0[2] + o0[3] * o0[3])) + ((o1[0] * o1[0] + o1[1] * o1[1]) + (o1[2] * o1[2] + o1[3] * o1[3])); }
;                 }
;                 if (!out) { ss += __shfl_xor(ss, 16); ss += __shfl_xor(ss, 32); if (fq == 0) ssqx[(size_t)row * 32 + un.pn * 4 + wc] = ss; }
.LBB0_1444:
	v_add_u32_e32 v16, 0xb0, v142
	s_waitcnt lgkmcnt(0)
	v_ashrrev_i32_e32 v17, 31, v16
	v_lshlrev_b64 v[18:19], 11, v[16:17]
	v_lshl_add_u64 v[18:19], v[18:19], 0, v[140:141]
	v_lshl_add_u64 v[20:21], v[18:19], 1, s[0:1]
	s_mov_b64 s[30:31], -1
	s_and_b64 vcc, exec, s[42:43]
	v_lshlrev_b32_e32 v22, 16, v226
	v_and_b32_e32 v23, 0xffff0000, v226
	v_lshlrev_b32_e32 v26, 16, v227
	v_and_b32_e32 v27, 0xffff0000, v227
	v_pk_add_f32 v[14:15], v[14:15], v[26:27]
	v_pk_add_f32 v[12:13], v[12:13], v[22:23]
	v_lshlrev_b32_e32 v22, 16, v228
	v_and_b32_e32 v23, 0xffff0000, v228
	v_lshlrev_b32_e32 v26, 16, v229
	v_and_b32_e32 v27, 0xffff0000, v229
	v_pk_add_f32 v[10:11], v[10:11], v[26:27]
	v_pk_add_f32 v[8:9], v[8:9], v[22:23]
	v_lshl_add_u64 v[22:23], v[18:19], 2, s[24:25]
	s_cbranch_vccnz .LBB0_1446
	s_mov_b64 s[30:31], 0
	global_store_dwordx4 v[22:23], v[12:15], off sc0 sc1
	global_store_dwordx4 v[22:23], v[8:11], off offset:16 sc0 sc1
.LBB0_1446:
	s_andn2_b64 vcc, exec, s[30:31]
	v_mov_b32_e32 v26, 0
	s_cbranch_vccnz .LBB0_1448
	v_cvt_pk_bf16_f32 v26, v12, v13
	v_cvt_pk_bf16_f32 v27, v14, v15
	v_cvt_pk_bf16_f32 v28, v8, v9
	v_cvt_pk_bf16_f32 v29, v10, v11
	global_store_dwordx4 v[20:21], v[26:29], off sc0 sc1
	v_mov_b32_e32 v21, v8
	v_mov_b32_e32 v8, v13
	v_mov_b32_e32 v13, v10
	v_mov_b32_e32 v10, v15
	v_mov_b32_e32 v20, v12
	v_pk_mul_f32 v[8:9], v[8:9], v[8:9]
	v_mov_b32_e32 v12, v14
	v_pk_mul_f32 v[10:11], v[10:11], v[10:11]
	v_pk_fma_f32 v[8:9], v[20:21], v[20:21], v[8:9]
	v_pk_fma_f32 v[10:11], v[12:13], v[12:13], v[10:11]
	s_nop 0
	v_pk_add_f32 v[8:9], v[8:9], v[10:11]
	s_nop 0
	v_add_f32_e32 v26, v8, v9

; __device__ __forceinline__ u32x4 pack8(f32x4 a, f32x4 b) { u32x4 w; w.x = pk2(a[0], a[1]); w.y = pk2(a[2], a[3]); w.z = pk2(b[0], b[1]); w.w = pk2(b[2], b[3]); return w; }
;     __device__ __forceinline__ void operator()(const f32x4 (&acc)[2][2][4][2], const Unit& un, int wr, int wc, int fr, int fq, int lane) const {
;     ...
;                 const int row = un.pm * 256 + ai * 128 + wr * 64 + m * 16 + fr; float ss = 0.f;
; #pragma unroll
;                 for (int bj = 0; bj < 2; ++bj) {
;                     const size_t off = (size_t)row * DM + c0 + bj * 128; const u32x4 xw = *(const u32x4*)(xb + off);
;                     const f32x4 o0 = (f32x4){bflo(xw.x), bfhi(xw.x), bflo(xw.y), bfhi(xw.y)} + acc[ai][bj][m][0], o1 = (f32x4){bflo(xw.z), bfhi(xw.z), bflo(xw.w), bfhi(xw.w)} + acc[ai][bj][m][1];
;                     if (out) { *(f32x4*)(out + off) = o0; *(f32x4*)(out + off + 4) = o1; }
;                     else { *(u32x4*)(xb + off) = pack8(o0, o1);
;                         ss += ((o0[0] * o0[0] + o0[1] * o0[1]) + (o0[2] * o0[2] + o0[3] * o0[3])) + ((o1[0] * o1[0] + o1[1] * o1[1]) + (o1[2] * o1[2] + o1[3] * o1[3])); }
;                 }
;                 if (!out) { ss += __shfl_xor(ss, 16); ss += __shfl_xor(ss, 32); if (fq == 0) ssqx[(size_t)row * 32 + un.pn * 4 + wc] = ss; }
.LBB0_1452:
	global_store_dwordx4 v[22:23], v[4:7], off offset:512 sc0 sc1
	global_store_dwordx4 v[22:23], v[0:3], off offset:528 sc0 sc1
	s_cbranch_execnz .LBB0_1450
.LBB0_1453:
	v_cvt_pk_bf16_f32 v10, v4, v5
	v_cvt_pk_bf16_f32 v11, v6, v7
	v_cvt_pk_bf16_f32 v12, v0, v1
	v_cvt_pk_bf16_f32 v13, v2, v3
	global_store_dwordx4 v[8:9], v[10:13], off sc0 sc1
	v_mov_b32_e32 v9, v0
	v_mov_b32_e32 v0, v5
	v_mov_b32_e32 v5, v2
	v_mov_b32_e32 v2, v7
	v_mov_b32_e32 v8, v4
	v_pk_mul_f32 v[0:1], v[0:1], v[0:1]
	v_mov_b32_e32 v4, v6
	v_pk_mul_f32 v[2:3], v[2:3], v[2:3]
	v_pk_fma_f32 v[0:1], v[8:9], v[8:9], v[0:1]
	v_pk_fma_f32 v[2:3], v[4:5], v[4:5], v[2:3]
	s_nop 0
	v_pk_add_f32 v[0:1], v[0:1], v[2:3]
	s_nop 0
	v_add_f32_e32 v0, v0, v1
	v_add_f32_e32 v26, v26, v0
	s_and_b64 vcc, exec, s[44:45]
	s_cbranch_vccnz .LBB0_1451
